# stack3 plus: GEMM K-loops drop the second of the two back-to-back lgkmcnt(0) waits around each pre-MFMA barrier (no LDS op between them)
# baseline (speedup 1.0000x reference)
; #define PG8_STAGE(bufoff, gbase, voff) do { _Pragma("unroll") for (int _i = 0; _i < 2; ++_i) \
;         __builtin_amdgcn_global_load_lds((const unsigned*)((const char*)(gbase) + (voff)[_i]), (LAS unsigned*)(lds + (bufoff) + ldsw + _i * 8192), 16, 0, 0); } while (0)
; #define PG8_LDA(dst, b, h) do { _Pragma("unroll") for (int m = 0; m < 4; ++m) _Pragma("unroll") for (int k = 0; k < 2; ++k) dst[m][k] = *(const LAS bf16x8*)(lds + PG8_SA(b, h) + aoff + m * 2048 + k * 1024); } while (0)
; #define PG8_LDB(dst, b, h) do { _Pragma("unroll") for (int n = 0; n < 2; ++n) _Pragma("unroll") for (int k = 0; k < 2; ++k) dst[n][k] = *(const LAS bf16x8*)(lds + PG8_SB(b, h) + boff + n * 2048 + k * 1024); } while (0)
; #define PG8_MMA(ai, bj, At, Bt) do { __builtin_amdgcn_s_setprio(1); _Pragma("unroll") for (int m = 0; m < 4; ++m) _Pragma("unroll") for (int n = 0; n < 2; ++n) _Pragma("unroll") for (int k = 0; k < 2; ++k) \
;         acc[ai][bj][m][n] = __builtin_amdgcn_mfma_f32_16x16x32_bf16(Bt[n][k], At[m][k], acc[ai][bj][m][n], 0, 0, 0); __builtin_amdgcn_s_setprio(0); } while (0)
; #define PG8_WAIT_V(n) asm volatile("s_waitcnt vmcnt(" #n ")" ::: "memory")
; #define PG8_BAR __builtin_amdgcn_s_barrier()
; template <class Epi, bool ALIGN_EPI>
; __device__ __forceinline__ void gemm_phase(LAS unsigned char* lds, const int tid, const Gemm g, const StaticOrder& S, const Epi& E) {
;     ...
;         for (int t = 0; t < nt; t += 2) {
;             if constexpr (Epi::HOOK) { if (t != 0 && (t & 7) == 0) E.hook(acc, cur, (t >> 3) - 1, wr, wc, fr, fq); }
;             const bool last = (t == nt - 2);
;             const char* a1 = cA + (size_t)(t + 1) * kstepA;
;             const char* a2 = last ? nA : cA + (size_t)(t + 2) * kstepA; const char* b2 = last ? nB : cB + (size_t)(t + 2) * kstepB;
;             const char* a3 = a2 + kstepA; const char* b3 = b2 + kstepB;
;             PG8_LDB(B0, 0, 0); PG8_LDB(B1, 0, 1); PG8_SCHED; PG8_LDA(At, 0, 0); PG8_STAGE(PG8_SA(1, 1), a1 + hstepA, voffA);
;             PG8_WAIT_V(8); PG8_WAIT_L(0); PG8_BAR; PG8_MMA(0, 0, At, B0); PG8_MMA(0, 1, At, B1); PG8_BAR; PG8_SCHED;
;             PG8_LDA(At, 0, 1); PG8_STAGE(PG8_SB(0, 0), b2, voffB); PG8_STAGE(PG8_SB(0, 1), b2 + hstepB, voffB); PG8_STAGE(PG8_SA(0, 0), a2, voffA);
;             PG8_WAIT_V(8); PG8_WAIT_L(0); PG8_BAR; PG8_MMA(1, 0, At, B0); PG8_MMA(1, 1, At, B1); PG8_BAR; PG8_SCHED;
.LBB0_113:
	s_add_i32 s90, s90, 2
	s_and_b64 s[34:35], exec, s[34:35]
	s_cselect_b32 s55, s23, s27
	s_cselect_b32 s54, s22, s25
	s_add_u32 s34, s92, 0x120000
	s_addc_u32 s35, s93, 0
	s_add_i32 s91, 0, 0x10000
	s_add_i32 s96, 0, 0x14000
	v_add_u32_e32 v148, s91, v175
	v_add_u32_e32 v164, s96, v175
	ds_read_b128 v[136:139], v148
	ds_read_b128 v[140:143], v148 offset:1024
	ds_read_b128 v[144:147], v148 offset:2048
	ds_read_b128 v[148:151], v148 offset:3072
	ds_read_b128 v[152:155], v164
	ds_read_b128 v[156:159], v164 offset:1024
	ds_read_b128 v[160:163], v164 offset:2048
	ds_read_b128 v[164:167], v164 offset:3072
	v_lshl_add_u64 v[172:173], s[30:31], 0, v[134:135]
	s_add_i32 m0, s56, 0xc000
	ds_read_b128 v[168:171], v177
	ds_read_b128 v[178:181], v177 offset:1024
	ds_read_b128 v[182:185], v177 offset:2048
	ds_read_b128 v[186:189], v177 offset:3072
	ds_read_b128 v[190:193], v177 offset:4096
	ds_read_b128 v[210:213], v177 offset:5120
	ds_read_b128 v[214:217], v177 offset:6144
	ds_read_b128 v[218:221], v177 offset:7168
	global_load_lds_dwordx4 v[172:173], off
	v_lshl_add_u64 v[172:173], s[30:31], 0, v[132:133]
	s_add_i32 m0, s56, 0xe000
	s_nop 0
	global_load_lds_dwordx4 v[172:173], off
	s_sub_u32 s98, s30, 0x4000
	s_subb_u32 s99, s31, 0
	v_lshl_add_u64 v[172:173], s[98:99], 0, v[134:135]
	s_mov_b32 m0, s70
	s_nop 0
	global_load_lds_dwordx4 v[172:173], off
	v_lshl_add_u64 v[172:173], s[98:99], 0, v[132:133]
	s_mov_b32 m0, s71
	s_nop 0
	global_load_lds_dwordx4 v[172:173], off
	s_waitcnt vmcnt(8)
	s_waitcnt lgkmcnt(0)
	s_barrier
	v_mfma_f32_16x16x32_bf16 v[126:129], v[136:139], v[168:171], v[126:129]
	v_mfma_f32_16x16x32_bf16 v[94:97], v[144:147], v[168:171], v[94:97]
	v_mfma_f32_16x16x32_bf16 v[122:125], v[136:139], v[182:185], v[122:125]
	v_mfma_f32_16x16x32_bf16 v[90:93], v[144:147], v[182:185], v[90:93]
	v_mfma_f32_16x16x32_bf16 v[118:121], v[136:139], v[190:193], v[118:121]
	v_mfma_f32_16x16x32_bf16 v[86:89], v[144:147], v[190:193], v[86:89]
	v_mfma_f32_16x16x32_bf16 v[114:117], v[136:139], v[214:217], v[114:117]
	v_mfma_f32_16x16x32_bf16 v[82:85], v[144:147], v[214:217], v[82:85]
	v_mfma_f32_16x16x32_bf16 v[126:129], v[140:143], v[178:181], v[126:129]
	v_mfma_f32_16x16x32_bf16 v[94:97], v[148:151], v[178:181], v[94:97]
	v_mfma_f32_16x16x32_bf16 v[122:125], v[140:143], v[186:189], v[122:125]
	v_mfma_f32_16x16x32_bf16 v[90:93], v[148:151], v[186:189], v[90:93]
	v_mfma_f32_16x16x32_bf16 v[118:121], v[140:143], v[210:213], v[118:121]
	v_mfma_f32_16x16x32_bf16 v[86:89], v[148:151], v[210:213], v[86:89]
	v_mfma_f32_16x16x32_bf16 v[114:117], v[140:143], v[218:221], v[114:117]
	v_mfma_f32_16x16x32_bf16 v[82:85], v[148:151], v[218:221], v[82:85]
	v_mfma_f32_16x16x32_bf16 v[62:65], v[152:155], v[168:171], v[62:65]
	v_mfma_f32_16x16x32_bf16 v[38:41], v[160:163], v[168:171], v[38:41]
	v_mfma_f32_16x16x32_bf16 v[58:61], v[152:155], v[182:185], v[58:61]
	v_mfma_f32_16x16x32_bf16 v[30:33], v[160:163], v[182:185], v[30:33]
	v_mfma_f32_16x16x32_bf16 v[54:57], v[152:155], v[190:193], v[54:57]
	v_mfma_f32_16x16x32_bf16 v[22:25], v[160:163], v[190:193], v[22:25]
	v_mfma_f32_16x16x32_bf16 v[50:53], v[152:155], v[214:217], v[50:53]
	v_mfma_f32_16x16x32_bf16 v[18:21], v[160:163], v[214:217], v[18:21]
	v_mfma_f32_16x16x32_bf16 v[62:65], v[156:159], v[178:181], v[62:65]
	v_mfma_f32_16x16x32_bf16 v[38:41], v[164:167], v[178:181], v[38:41]
	v_mfma_f32_16x16x32_bf16 v[58:61], v[156:159], v[186:189], v[58:61]
	v_mfma_f32_16x16x32_bf16 v[30:33], v[164:167], v[186:189], v[30:33]
	v_mfma_f32_16x16x32_bf16 v[54:57], v[156:159], v[210:213], v[54:57]
	v_mfma_f32_16x16x32_bf16 v[22:25], v[164:167], v[210:213], v[22:25]
	v_mfma_f32_16x16x32_bf16 v[50:53], v[156:159], v[218:221], v[50:53]
	v_mfma_f32_16x16x32_bf16 v[18:21], v[164:167], v[218:221], v[18:21]
	s_barrier
	s_add_i32 s91, s91, s29
	v_lshl_add_u64 v[172:173], s[54:55], 0, v[0:1]
	s_mov_b32 m0, s91
	ds_read_b128 v[168:171], v177 offset:16384
	ds_read_b128 v[178:181], v177 offset:17408
	ds_read_b128 v[182:185], v177 offset:18432
	ds_read_b128 v[186:189], v177 offset:19456
	ds_read_b128 v[190:193], v177 offset:20480
	ds_read_b128 v[210:213], v177 offset:21504
	ds_read_b128 v[214:217], v177 offset:22528
	ds_read_b128 v[218:221], v177 offset:23552
	global_load_lds_dwordx4 v[172:173], off
	s_add_i32 m0, s91, 0x2000
	s_add_u32 s94, s54, 0x4000
	v_lshl_add_u64 v[172:173], s[54:55], 0, v[130:131]
	s_addc_u32 s95, s55, 0
	s_add_i32 s91, s96, s29
	global_load_lds_dwordx4 v[172:173], off
	v_lshl_add_u64 v[172:173], s[94:95], 0, v[0:1]
	s_mov_b32 m0, s91
	s_nop 0
	global_load_lds_dwordx4 v[172:173], off
	v_lshl_add_u64 v[172:173], s[94:95], 0, v[130:131]
	s_add_i32 m0, s91, 0x2000
	s_nop 0
	global_load_lds_dwordx4 v[172:173], off
	s_waitcnt vmcnt(4)
	s_waitcnt lgkmcnt(0)
	s_barrier
; #define PG8_STAGE(bufoff, gbase, voff) do { _Pragma("unroll") for (int _i = 0; _i < 2; ++_i) \
;         __builtin_amdgcn_global_load_lds((const unsigned*)((const char*)(gbase) + (voff)[_i]), (LAS unsigned*)(lds + (bufoff) + ldsw + _i * 8192), 16, 0, 0); } while (0)
; #define PG8_LDA(dst, b, h) do { _Pragma("unroll") for (int m = 0; m < 4; ++m) _Pragma("unroll") for (int k = 0; k < 2; ++k) dst[m][k] = *(const LAS bf16x8*)(lds + PG8_SA(b, h) + aoff + m * 2048 + k * 1024); } while (0)
; #define PG8_LDB(dst, b, h) do { _Pragma("unroll") for (int n = 0; n < 2; ++n) _Pragma("unroll") for (int k = 0; k < 2; ++k) dst[n][k] = *(const LAS bf16x8*)(lds + PG8_SB(b, h) + boff + n * 2048 + k * 1024); } while (0)
; #define PG8_MMA(ai, bj, At, Bt) do { __builtin_amdgcn_s_setprio(1); _Pragma("unroll") for (int m = 0; m < 4; ++m) _Pragma("unroll") for (int n = 0; n < 2; ++n) _Pragma("unroll") for (int k = 0; k < 2; ++k) \
;         acc[ai][bj][m][n] = __builtin_amdgcn_mfma_f32_16x16x32_bf16(Bt[n][k], At[m][k], acc[ai][bj][m][n], 0, 0, 0); __builtin_amdgcn_s_setprio(0); } while (0)
; #define PG8_WAIT_V(n) asm volatile("s_waitcnt vmcnt(" #n ")" ::: "memory")
; #define PG8_WAIT_L(n) asm volatile("s_waitcnt lgkmcnt(" #n ")" ::: "memory")
; #define PG8_BAR __builtin_amdgcn_s_barrier()
; #define PG8_SCHED __builtin_amdgcn_sched_barrier(0)
; template <class Epi, bool ALIGN_EPI>
; __device__ __forceinline__ void gemm_phase(LAS unsigned char* lds, const int tid, const Gemm g, const StaticOrder& S, const Epi& E) {
;     ...
;             PG8_LDA(At, 0, 1); PG8_STAGE(PG8_SB(0, 0), b2, voffB); PG8_STAGE(PG8_SB(0, 1), b2 + hstepB, voffB); PG8_STAGE(PG8_SA(0, 0), a2, voffA);
;             PG8_WAIT_V(8); PG8_WAIT_L(0); PG8_BAR; PG8_MMA(1, 0, At, B0); PG8_MMA(1, 1, At, B1); PG8_BAR; PG8_SCHED;
;             PG8_LDB(B0, 1, 0); PG8_LDB(B1, 1, 1); PG8_SCHED; PG8_LDA(At, 1, 0); PG8_STAGE(PG8_SA(0, 1), a2 + hstepA, voffA);
;             PG8_WAIT_V(8); PG8_WAIT_L(0); PG8_BAR; PG8_MMA(0, 0, At, B0); PG8_MMA(0, 1, At, B1); PG8_BAR; PG8_SCHED;
	v_mfma_f32_16x16x32_bf16 v[110:113], v[136:139], v[168:171], v[110:113]
	v_mfma_f32_16x16x32_bf16 v[78:81], v[144:147], v[168:171], v[78:81]
	v_mfma_f32_16x16x32_bf16 v[106:109], v[136:139], v[182:185], v[106:109]
	v_mfma_f32_16x16x32_bf16 v[74:77], v[144:147], v[182:185], v[74:77]
	v_mfma_f32_16x16x32_bf16 v[102:105], v[136:139], v[190:193], v[102:105]
	v_mfma_f32_16x16x32_bf16 v[70:73], v[144:147], v[190:193], v[70:73]
	v_mfma_f32_16x16x32_bf16 v[98:101], v[136:139], v[214:217], v[98:101]
	v_mfma_f32_16x16x32_bf16 v[66:69], v[144:147], v[214:217], v[66:69]
	v_mfma_f32_16x16x32_bf16 v[110:113], v[140:143], v[178:181], v[110:113]
	v_mfma_f32_16x16x32_bf16 v[78:81], v[148:151], v[178:181], v[78:81]
	v_mfma_f32_16x16x32_bf16 v[106:109], v[140:143], v[186:189], v[106:109]
	v_mfma_f32_16x16x32_bf16 v[74:77], v[148:151], v[186:189], v[74:77]
	v_mfma_f32_16x16x32_bf16 v[102:105], v[140:143], v[210:213], v[102:105]
	v_mfma_f32_16x16x32_bf16 v[70:73], v[148:151], v[210:213], v[70:73]
	v_mfma_f32_16x16x32_bf16 v[98:101], v[140:143], v[218:221], v[98:101]
	v_mfma_f32_16x16x32_bf16 v[66:69], v[148:151], v[218:221], v[66:69]
	v_mfma_f32_16x16x32_bf16 v[46:49], v[152:155], v[168:171], v[46:49]
	v_mfma_f32_16x16x32_bf16 v[14:17], v[160:163], v[168:171], v[14:17]
	v_mfma_f32_16x16x32_bf16 v[42:45], v[152:155], v[182:185], v[42:45]
	v_mfma_f32_16x16x32_bf16 v[10:13], v[160:163], v[182:185], v[10:13]
	v_mfma_f32_16x16x32_bf16 v[34:37], v[152:155], v[190:193], v[34:37]
	v_mfma_f32_16x16x32_bf16 v[6:9], v[160:163], v[190:193], v[6:9]
	v_mfma_f32_16x16x32_bf16 v[26:29], v[152:155], v[214:217], v[26:29]
	v_mfma_f32_16x16x32_bf16 v[2:5], v[160:163], v[214:217], v[2:5]
	v_mfma_f32_16x16x32_bf16 v[46:49], v[156:159], v[178:181], v[46:49]
	v_mfma_f32_16x16x32_bf16 v[14:17], v[164:167], v[178:181], v[14:17]
	v_mfma_f32_16x16x32_bf16 v[42:45], v[156:159], v[186:189], v[42:45]
	v_mfma_f32_16x16x32_bf16 v[10:13], v[164:167], v[186:189], v[10:13]
	v_mfma_f32_16x16x32_bf16 v[34:37], v[156:159], v[210:213], v[34:37]
	v_mfma_f32_16x16x32_bf16 v[6:9], v[164:167], v[210:213], v[6:9]
	v_mfma_f32_16x16x32_bf16 v[26:29], v[156:159], v[218:221], v[26:29]
	v_mfma_f32_16x16x32_bf16 v[2:5], v[164:167], v[218:221], v[2:5]
	s_barrier
	s_add_i32 s91, 0, 0x18000
	s_add_i32 s94, 0, 0x1c000
	v_add_u32_e32 v148, s91, v175
	v_add_u32_e32 v164, s94, v175
	ds_read_b128 v[136:139], v148
	ds_read_b128 v[140:143], v148 offset:1024
	ds_read_b128 v[144:147], v148 offset:2048
	ds_read_b128 v[148:151], v148 offset:3072
	ds_read_b128 v[152:155], v164
	ds_read_b128 v[156:159], v164 offset:1024
	ds_read_b128 v[160:163], v164 offset:2048
	ds_read_b128 v[164:167], v164 offset:3072
	v_lshl_add_u64 v[172:173], s[92:93], 0, v[0:1]
	s_mov_b32 m0, s56
	s_nop 0
	global_load_lds_dwordx4 v[172:173], off
	v_lshl_add_u64 v[172:173], s[92:93], 0, v[130:131]
	s_mov_b32 m0, s58
	s_nop 0
	global_load_lds_dwordx4 v[172:173], off
	s_add_u32 s92, s92, 0x4000
	s_addc_u32 s93, s93, 0
	s_mov_b32 m0, s63
	v_lshl_add_u64 v[172:173], s[92:93], 0, v[0:1]
	ds_read_b128 v[168:171], v177 offset:32768
	ds_read_b128 v[178:181], v177 offset:33792
	ds_read_b128 v[182:185], v177 offset:34816
	ds_read_b128 v[186:189], v177 offset:35840
	ds_read_b128 v[190:193], v177 offset:36864
	ds_read_b128 v[210:213], v177 offset:37888
	ds_read_b128 v[214:217], v177 offset:38912
	ds_read_b128 v[218:221], v177 offset:39936
	global_load_lds_dwordx4 v[172:173], off
	v_lshl_add_u64 v[172:173], s[92:93], 0, v[130:131]
	s_mov_b32 m0, s64
	s_nop 0
	global_load_lds_dwordx4 v[172:173], off
	s_waitcnt vmcnt(8)
	s_waitcnt lgkmcnt(0)
	s_barrier
; #define PG8_STAGE(bufoff, gbase, voff) do { _Pragma("unroll") for (int _i = 0; _i < 2; ++_i) \
;         __builtin_amdgcn_global_load_lds((const unsigned*)((const char*)(gbase) + (voff)[_i]), (LAS unsigned*)(lds + (bufoff) + ldsw + _i * 8192), 16, 0, 0); } while (0)
; #define PG8_LDA(dst, b, h) do { _Pragma("unroll") for (int m = 0; m < 4; ++m) _Pragma("unroll") for (int k = 0; k < 2; ++k) dst[m][k] = *(const LAS bf16x8*)(lds + PG8_SA(b, h) + aoff + m * 2048 + k * 1024); } while (0)
; #define PG8_LDB(dst, b, h) do { _Pragma("unroll") for (int n = 0; n < 2; ++n) _Pragma("unroll") for (int k = 0; k < 2; ++k) dst[n][k] = *(const LAS bf16x8*)(lds + PG8_SB(b, h) + boff + n * 2048 + k * 1024); } while (0)
; #define PG8_MMA(ai, bj, At, Bt) do { __builtin_amdgcn_s_setprio(1); _Pragma("unroll") for (int m = 0; m < 4; ++m) _Pragma("unroll") for (int n = 0; n < 2; ++n) _Pragma("unroll") for (int k = 0; k < 2; ++k) \
;         acc[ai][bj][m][n] = __builtin_amdgcn_mfma_f32_16x16x32_bf16(Bt[n][k], At[m][k], acc[ai][bj][m][n], 0, 0, 0); __builtin_amdgcn_s_setprio(0); } while (0)
; #define PG8_WAIT_V(n) asm volatile("s_waitcnt vmcnt(" #n ")" ::: "memory")
; #define PG8_WAIT_L(n) asm volatile("s_waitcnt lgkmcnt(" #n ")" ::: "memory")
; #define PG8_BAR __builtin_amdgcn_s_barrier()
; #define PG8_SCHED __builtin_amdgcn_sched_barrier(0)
; template <class Epi, bool ALIGN_EPI>
; __device__ __forceinline__ void gemm_phase(LAS unsigned char* lds, const int tid, const Gemm g, const StaticOrder& S, const Epi& E) {
;     ...
;             PG8_LDB(B0, 1, 0); PG8_LDB(B1, 1, 1); PG8_SCHED; PG8_LDA(At, 1, 0); PG8_STAGE(PG8_SA(0, 1), a2 + hstepA, voffA);
;             PG8_WAIT_V(8); PG8_WAIT_L(0); PG8_BAR; PG8_MMA(0, 0, At, B0); PG8_MMA(0, 1, At, B1); PG8_BAR; PG8_SCHED;
;             PG8_LDA(At, 1, 1); PG8_STAGE(PG8_SB(1, 0), b3, voffB); PG8_STAGE(PG8_SB(1, 1), b3 + hstepB, voffB); PG8_STAGE(PG8_SA(1, 0), a3, voffA);
;             PG8_WAIT_V(8); PG8_WAIT_L(0); PG8_BAR; PG8_MMA(1, 0, At, B0); PG8_MMA(1, 1, At, B1); PG8_BAR; PG8_SCHED;
;         }
	v_mfma_f32_16x16x32_bf16 v[126:129], v[136:139], v[168:171], v[126:129]
	v_mfma_f32_16x16x32_bf16 v[94:97], v[144:147], v[168:171], v[94:97]
	v_mfma_f32_16x16x32_bf16 v[122:125], v[136:139], v[182:185], v[122:125]
	v_mfma_f32_16x16x32_bf16 v[90:93], v[144:147], v[182:185], v[90:93]
	v_mfma_f32_16x16x32_bf16 v[118:121], v[136:139], v[190:193], v[118:121]
	v_mfma_f32_16x16x32_bf16 v[86:89], v[144:147], v[190:193], v[86:89]
	v_mfma_f32_16x16x32_bf16 v[114:117], v[136:139], v[214:217], v[114:117]
	v_mfma_f32_16x16x32_bf16 v[82:85], v[144:147], v[214:217], v[82:85]
	v_mfma_f32_16x16x32_bf16 v[126:129], v[140:143], v[178:181], v[126:129]
	v_mfma_f32_16x16x32_bf16 v[94:97], v[148:151], v[178:181], v[94:97]
	v_mfma_f32_16x16x32_bf16 v[122:125], v[140:143], v[186:189], v[122:125]
	v_mfma_f32_16x16x32_bf16 v[90:93], v[148:151], v[186:189], v[90:93]
	v_mfma_f32_16x16x32_bf16 v[118:121], v[140:143], v[210:213], v[118:121]
	v_mfma_f32_16x16x32_bf16 v[86:89], v[148:151], v[210:213], v[86:89]
	v_mfma_f32_16x16x32_bf16 v[114:117], v[140:143], v[218:221], v[114:117]
	v_mfma_f32_16x16x32_bf16 v[82:85], v[148:151], v[218:221], v[82:85]
	v_mfma_f32_16x16x32_bf16 v[62:65], v[152:155], v[168:171], v[62:65]
	v_mfma_f32_16x16x32_bf16 v[38:41], v[160:163], v[168:171], v[38:41]
	v_mfma_f32_16x16x32_bf16 v[58:61], v[152:155], v[182:185], v[58:61]
	v_mfma_f32_16x16x32_bf16 v[30:33], v[160:163], v[182:185], v[30:33]
	v_mfma_f32_16x16x32_bf16 v[54:57], v[152:155], v[190:193], v[54:57]
	v_mfma_f32_16x16x32_bf16 v[22:25], v[160:163], v[190:193], v[22:25]
	v_mfma_f32_16x16x32_bf16 v[50:53], v[152:155], v[214:217], v[50:53]
	v_mfma_f32_16x16x32_bf16 v[18:21], v[160:163], v[214:217], v[18:21]
	v_mfma_f32_16x16x32_bf16 v[62:65], v[156:159], v[178:181], v[62:65]
	v_mfma_f32_16x16x32_bf16 v[38:41], v[164:167], v[178:181], v[38:41]
	v_mfma_f32_16x16x32_bf16 v[58:61], v[156:159], v[186:189], v[58:61]
	v_mfma_f32_16x16x32_bf16 v[30:33], v[164:167], v[186:189], v[30:33]
	v_mfma_f32_16x16x32_bf16 v[54:57], v[156:159], v[210:213], v[54:57]
	v_mfma_f32_16x16x32_bf16 v[22:25], v[164:167], v[210:213], v[22:25]
	v_mfma_f32_16x16x32_bf16 v[50:53], v[156:159], v[218:221], v[50:53]
	v_mfma_f32_16x16x32_bf16 v[18:21], v[164:167], v[218:221], v[18:21]
	s_barrier
	s_add_u32 s92, s54, 0x40000
	s_addc_u32 s93, s55, 0
	s_add_i32 s91, s91, s29
	v_lshl_add_u64 v[172:173], s[92:93], 0, v[0:1]
	s_mov_b32 m0, s91
	ds_read_b128 v[168:171], v177 offset:49152
	ds_read_b128 v[178:181], v177 offset:50176
	ds_read_b128 v[182:185], v177 offset:51200
	ds_read_b128 v[186:189], v177 offset:52224
	ds_read_b128 v[190:193], v177 offset:53248
	ds_read_b128 v[210:213], v177 offset:54272
	ds_read_b128 v[214:217], v177 offset:55296
	ds_read_b128 v[218:221], v177 offset:56320
	global_load_lds_dwordx4 v[172:173], off
	s_add_i32 m0, s91, 0x2000
	s_add_u32 s54, s54, 0x44000
	v_lshl_add_u64 v[172:173], s[92:93], 0, v[130:131]
	s_addc_u32 s55, s55, 0
	s_add_i32 s91, s94, s29
	global_load_lds_dwordx4 v[172:173], off
	v_lshl_add_u64 v[172:173], s[54:55], 0, v[0:1]
	s_mov_b32 m0, s91
	s_nop 0
	global_load_lds_dwordx4 v[172:173], off
	v_lshl_add_u64 v[172:173], s[54:55], 0, v[130:131]
	s_add_i32 m0, s91, 0x2000
	s_nop 0
	global_load_lds_dwordx4 v[172:173], off
	s_waitcnt vmcnt(4)
	s_waitcnt lgkmcnt(0)
	s_barrier
	v_mfma_f32_16x16x32_bf16 v[110:113], v[136:139], v[168:171], v[110:113]
	v_mfma_f32_16x16x32_bf16 v[78:81], v[144:147], v[168:171], v[78:81]
	v_mfma_f32_16x16x32_bf16 v[106:109], v[136:139], v[182:185], v[106:109]
	v_mfma_f32_16x16x32_bf16 v[74:77], v[144:147], v[182:185], v[74:77]
	v_mfma_f32_16x16x32_bf16 v[102:105], v[136:139], v[190:193], v[102:105]
	v_mfma_f32_16x16x32_bf16 v[70:73], v[144:147], v[190:193], v[70:73]
	v_mfma_f32_16x16x32_bf16 v[98:101], v[136:139], v[214:217], v[98:101]
	v_mfma_f32_16x16x32_bf16 v[66:69], v[144:147], v[214:217], v[66:69]
	v_mfma_f32_16x16x32_bf16 v[110:113], v[140:143], v[178:181], v[110:113]
	v_mfma_f32_16x16x32_bf16 v[78:81], v[148:151], v[178:181], v[78:81]
	v_mfma_f32_16x16x32_bf16 v[106:109], v[140:143], v[186:189], v[106:109]
	v_mfma_f32_16x16x32_bf16 v[74:77], v[148:151], v[186:189], v[74:77]
	v_mfma_f32_16x16x32_bf16 v[102:105], v[140:143], v[210:213], v[102:105]
	v_mfma_f32_16x16x32_bf16 v[70:73], v[148:151], v[210:213], v[70:73]
	v_mfma_f32_16x16x32_bf16 v[98:101], v[140:143], v[218:221], v[98:101]
	v_mfma_f32_16x16x32_bf16 v[66:69], v[148:151], v[218:221], v[66:69]
	v_mfma_f32_16x16x32_bf16 v[46:49], v[152:155], v[168:171], v[46:49]
	v_mfma_f32_16x16x32_bf16 v[14:17], v[160:163], v[168:171], v[14:17]
	v_mfma_f32_16x16x32_bf16 v[42:45], v[152:155], v[182:185], v[42:45]
	v_mfma_f32_16x16x32_bf16 v[10:13], v[160:163], v[182:185], v[10:13]
	v_mfma_f32_16x16x32_bf16 v[34:37], v[152:155], v[190:193], v[34:37]
	v_mfma_f32_16x16x32_bf16 v[6:9], v[160:163], v[190:193], v[6:9]
	v_mfma_f32_16x16x32_bf16 v[26:29], v[152:155], v[214:217], v[26:29]
	v_mfma_f32_16x16x32_bf16 v[2:5], v[160:163], v[214:217], v[2:5]
	v_mfma_f32_16x16x32_bf16 v[46:49], v[156:159], v[178:181], v[46:49]
	v_mfma_f32_16x16x32_bf16 v[14:17], v[164:167], v[178:181], v[14:17]
	v_mfma_f32_16x16x32_bf16 v[42:45], v[156:159], v[186:189], v[42:45]
	v_mfma_f32_16x16x32_bf16 v[10:13], v[164:167], v[186:189], v[10:13]
	v_mfma_f32_16x16x32_bf16 v[34:37], v[156:159], v[210:213], v[34:37]
	v_mfma_f32_16x16x32_bf16 v[6:9], v[164:167], v[210:213], v[6:9]
	v_mfma_f32_16x16x32_bf16 v[26:29], v[156:159], v[218:221], v[26:29]
	v_mfma_f32_16x16x32_bf16 v[2:5], v[164:167], v[218:221], v[2:5]
	s_barrier
	s_add_u32 s25, s25, 0x80000
	s_addc_u32 s27, s27, 0
	s_add_u32 s30, s30, 0x240000
	s_addc_u32 s31, s31, 0
	s_cmp_ge_u32 s90, s17
	s_cbranch_scc1 .LBB0_116

; #define PG8_STAGE(bufoff, gbase, voff) do { _Pragma("unroll") for (int _i = 0; _i < 2; ++_i) \
;         __builtin_amdgcn_global_load_lds((const unsigned*)((const char*)(gbase) + (voff)[_i]), (LAS unsigned*)(lds + (bufoff) + ldsw + _i * 8192), 16, 0, 0); } while (0)
; #define PG8_LDA(dst, b, h) do { _Pragma("unroll") for (int m = 0; m < 4; ++m) _Pragma("unroll") for (int k = 0; k < 2; ++k) dst[m][k] = *(const LAS bf16x8*)(lds + PG8_SA(b, h) + aoff + m * 2048 + k * 1024); } while (0)
; #define PG8_LDB(dst, b, h) do { _Pragma("unroll") for (int n = 0; n < 2; ++n) _Pragma("unroll") for (int k = 0; k < 2; ++k) dst[n][k] = *(const LAS bf16x8*)(lds + PG8_SB(b, h) + boff + n * 2048 + k * 1024); } while (0)
; #define PG8_MMA(ai, bj, At, Bt) do { __builtin_amdgcn_s_setprio(1); _Pragma("unroll") for (int m = 0; m < 4; ++m) _Pragma("unroll") for (int n = 0; n < 2; ++n) _Pragma("unroll") for (int k = 0; k < 2; ++k) \
;         acc[ai][bj][m][n] = __builtin_amdgcn_mfma_f32_16x16x32_bf16(Bt[n][k], At[m][k], acc[ai][bj][m][n], 0, 0, 0); __builtin_amdgcn_s_setprio(0); } while (0)
; #define PG8_WAIT_V(n) asm volatile("s_waitcnt vmcnt(" #n ")" ::: "memory")
; #define PG8_WAIT_L(n) asm volatile("s_waitcnt lgkmcnt(" #n ")" ::: "memory")
; #define PG8_BAR __builtin_amdgcn_s_barrier()
; #define PG8_SCHED __builtin_amdgcn_sched_barrier(0)
; template <class Epi, bool ALIGN_EPI>
; __device__ __forceinline__ void gemm_phase(LAS unsigned char* lds, const int tid, const Gemm g, const StaticOrder& S, const Epi& E) {
;     ...
;             const bool last = (t == nt - 2);
;             const char* a1 = cA + (size_t)(t + 1) * kstepA;
;             const char* a2 = last ? nA : cA + (size_t)(t + 2) * kstepA; const char* b2 = last ? nB : cB + (size_t)(t + 2) * kstepB;
;             const char* a3 = a2 + kstepA; const char* b3 = b2 + kstepB;
;             PG8_LDB(B0, 0, 0); PG8_LDB(B1, 0, 1); PG8_SCHED; PG8_LDA(At, 0, 0); PG8_STAGE(PG8_SA(1, 1), a1 + hstepA, voffA);
;             PG8_WAIT_V(8); PG8_WAIT_L(0); PG8_BAR; PG8_MMA(0, 0, At, B0); PG8_MMA(0, 1, At, B1); PG8_BAR; PG8_SCHED;
;             PG8_LDA(At, 0, 1); PG8_STAGE(PG8_SB(0, 0), b2, voffB); PG8_STAGE(PG8_SB(0, 1), b2 + hstepB, voffB); PG8_STAGE(PG8_SA(0, 0), a2, voffA);
;             PG8_WAIT_V(8); PG8_WAIT_L(0); PG8_BAR; PG8_MMA(1, 0, At, B0); PG8_MMA(1, 1, At, B1); PG8_BAR; PG8_SCHED;
.LBB0_143:
	s_add_u32 s26, s24, 0xfff80080
	s_addc_u32 s27, s25, -1
	s_add_i32 s68, 0, 0x10000
	s_cmp_eq_u32 s67, 28
	s_cselect_b32 s29, s19, s27
	s_cselect_b32 s28, s18, s26
	v_add_u32_e32 v142, s68, v145
	s_cselect_b32 s27, s21, s17
	s_cselect_b32 s26, s20, s15
	s_add_i32 s70, 0, 0x14000
	ds_read_b128 v[148:151], v142
	ds_read_b128 v[152:155], v142 offset:1024
	ds_read_b128 v[156:159], v142 offset:2048
	ds_read_b128 v[160:163], v142 offset:3072
	v_add_u32_e32 v142, s70, v145
	ds_read_b128 v[164:167], v142
	ds_read_b128 v[168:171], v142 offset:1024
	ds_read_b128 v[172:175], v142 offset:2048
	ds_read_b128 v[176:179], v142 offset:3072
	v_lshl_add_u64 v[142:143], s[24:25], 0, v[140:141]
	s_add_i32 m0, s23, 0xc000
	ds_read_b128 v[180:183], v146
	ds_read_b128 v[184:187], v146 offset:1024
	ds_read_b128 v[188:191], v146 offset:2048
	ds_read_b128 v[192:195], v146 offset:3072
	ds_read_b128 v[210:213], v146 offset:4096
	ds_read_b128 v[214:217], v146 offset:5120
	ds_read_b128 v[218:221], v146 offset:6144
	ds_read_b128 v[222:225], v146 offset:7168
	global_load_lds_dwordx4 v[142:143], off
	v_lshl_add_u64 v[142:143], s[24:25], 0, v[138:139]
	s_add_i32 m0, s23, 0xe000
	s_nop 0
	global_load_lds_dwordx4 v[142:143], off
	s_sub_u32 s98, s24, 0x80000
	s_subb_u32 s99, s25, 0
	v_lshl_add_u64 v[142:143], s[98:99], 0, v[140:141]
	s_mov_b32 m0, s56
	s_nop 0
	global_load_lds_dwordx4 v[142:143], off
	v_lshl_add_u64 v[142:143], s[98:99], 0, v[138:139]
	s_mov_b32 m0, s58
	s_nop 0
	global_load_lds_dwordx4 v[142:143], off
	s_waitcnt vmcnt(8)
	s_waitcnt lgkmcnt(0)
	s_barrier
	v_mfma_f32_16x16x32_bf16 v[126:129], v[148:151], v[180:183], v[126:129]
	v_mfma_f32_16x16x32_bf16 v[122:125], v[156:159], v[180:183], v[122:125]
	v_mfma_f32_16x16x32_bf16 v[110:113], v[148:151], v[188:191], v[110:113]
	v_mfma_f32_16x16x32_bf16 v[106:109], v[156:159], v[188:191], v[106:109]
	v_mfma_f32_16x16x32_bf16 v[94:97], v[148:151], v[210:213], v[94:97]
	v_mfma_f32_16x16x32_bf16 v[90:93], v[156:159], v[210:213], v[90:93]
	v_mfma_f32_16x16x32_bf16 v[78:81], v[148:151], v[218:221], v[78:81]
	v_mfma_f32_16x16x32_bf16 v[74:77], v[156:159], v[218:221], v[74:77]
	v_mfma_f32_16x16x32_bf16 v[126:129], v[152:155], v[184:187], v[126:129]
	v_mfma_f32_16x16x32_bf16 v[122:125], v[160:163], v[184:187], v[122:125]
	v_mfma_f32_16x16x32_bf16 v[110:113], v[152:155], v[192:195], v[110:113]
	v_mfma_f32_16x16x32_bf16 v[106:109], v[160:163], v[192:195], v[106:109]
	v_mfma_f32_16x16x32_bf16 v[94:97], v[152:155], v[214:217], v[94:97]
	v_mfma_f32_16x16x32_bf16 v[90:93], v[160:163], v[214:217], v[90:93]
	v_mfma_f32_16x16x32_bf16 v[78:81], v[152:155], v[222:225], v[78:81]
	v_mfma_f32_16x16x32_bf16 v[74:77], v[160:163], v[222:225], v[74:77]
	v_mfma_f32_16x16x32_bf16 v[118:121], v[164:167], v[180:183], v[118:121]
	v_mfma_f32_16x16x32_bf16 v[114:117], v[172:175], v[180:183], v[114:117]
	v_mfma_f32_16x16x32_bf16 v[102:105], v[164:167], v[188:191], v[102:105]
	v_mfma_f32_16x16x32_bf16 v[98:101], v[172:175], v[188:191], v[98:101]
	v_mfma_f32_16x16x32_bf16 v[86:89], v[164:167], v[210:213], v[86:89]
	v_mfma_f32_16x16x32_bf16 v[82:85], v[172:175], v[210:213], v[82:85]
	v_mfma_f32_16x16x32_bf16 v[70:73], v[164:167], v[218:221], v[70:73]
	v_mfma_f32_16x16x32_bf16 v[66:69], v[172:175], v[218:221], v[66:69]
	v_mfma_f32_16x16x32_bf16 v[118:121], v[168:171], v[184:187], v[118:121]
	v_mfma_f32_16x16x32_bf16 v[114:117], v[176:179], v[184:187], v[114:117]
	v_mfma_f32_16x16x32_bf16 v[102:105], v[168:171], v[192:195], v[102:105]
	v_mfma_f32_16x16x32_bf16 v[98:101], v[176:179], v[192:195], v[98:101]
	v_mfma_f32_16x16x32_bf16 v[86:89], v[168:171], v[214:217], v[86:89]
	v_mfma_f32_16x16x32_bf16 v[82:85], v[176:179], v[214:217], v[82:85]
	v_mfma_f32_16x16x32_bf16 v[70:73], v[168:171], v[222:225], v[70:73]
	v_mfma_f32_16x16x32_bf16 v[66:69], v[176:179], v[222:225], v[66:69]
	s_barrier
	s_add_i32 s68, s68, s30
	v_lshl_add_u64 v[142:143], s[26:27], 0, v[0:1]
	s_mov_b32 m0, s68
	ds_read_b128 v[180:183], v146 offset:16384
	ds_read_b128 v[184:187], v146 offset:17408
	ds_read_b128 v[188:191], v146 offset:18432
	ds_read_b128 v[192:195], v146 offset:19456
	ds_read_b128 v[210:213], v146 offset:20480
	ds_read_b128 v[214:217], v146 offset:21504
	ds_read_b128 v[218:221], v146 offset:22528
	ds_read_b128 v[222:225], v146 offset:23552
	global_load_lds_dwordx4 v[142:143], off
	s_add_i32 m0, s68, 0x2000
	s_add_u32 s68, s26, 0x80000
	v_lshl_add_u64 v[240:241], s[26:27], 0, v[130:131]
	s_addc_u32 s69, s27, 0
	s_add_i32 s70, s70, s30
	global_load_lds_dwordx4 v[240:241], off
	v_lshl_add_u64 v[242:243], s[68:69], 0, v[0:1]
	s_mov_b32 m0, s70
	v_lshl_add_u64 v[244:245], s[28:29], 0, v[132:133]
	global_load_lds_dwordx4 v[242:243], off
	v_lshl_add_u64 v[242:243], s[68:69], 0, v[130:131]
	s_add_i32 m0, s70, 0x2000
	s_nop 0
	global_load_lds_dwordx4 v[242:243], off
	v_lshl_add_u64 v[242:243], s[28:29], 0, v[134:135]
	s_waitcnt vmcnt(4)
	s_waitcnt lgkmcnt(0)
	s_barrier
; #define PG8_STAGE(bufoff, gbase, voff) do { _Pragma("unroll") for (int _i = 0; _i < 2; ++_i) \
;         __builtin_amdgcn_global_load_lds((const unsigned*)((const char*)(gbase) + (voff)[_i]), (LAS unsigned*)(lds + (bufoff) + ldsw + _i * 8192), 16, 0, 0); } while (0)
; #define PG8_LDA(dst, b, h) do { _Pragma("unroll") for (int m = 0; m < 4; ++m) _Pragma("unroll") for (int k = 0; k < 2; ++k) dst[m][k] = *(const LAS bf16x8*)(lds + PG8_SA(b, h) + aoff + m * 2048 + k * 1024); } while (0)
; #define PG8_LDB(dst, b, h) do { _Pragma("unroll") for (int n = 0; n < 2; ++n) _Pragma("unroll") for (int k = 0; k < 2; ++k) dst[n][k] = *(const LAS bf16x8*)(lds + PG8_SB(b, h) + boff + n * 2048 + k * 1024); } while (0)
; #define PG8_MMA(ai, bj, At, Bt) do { __builtin_amdgcn_s_setprio(1); _Pragma("unroll") for (int m = 0; m < 4; ++m) _Pragma("unroll") for (int n = 0; n < 2; ++n) _Pragma("unroll") for (int k = 0; k < 2; ++k) \
;         acc[ai][bj][m][n] = __builtin_amdgcn_mfma_f32_16x16x32_bf16(Bt[n][k], At[m][k], acc[ai][bj][m][n], 0, 0, 0); __builtin_amdgcn_s_setprio(0); } while (0)
; #define PG8_WAIT_V(n) asm volatile("s_waitcnt vmcnt(" #n ")" ::: "memory")
; #define PG8_WAIT_L(n) asm volatile("s_waitcnt lgkmcnt(" #n ")" ::: "memory")
; #define PG8_BAR __builtin_amdgcn_s_barrier()
; #define PG8_SCHED __builtin_amdgcn_sched_barrier(0)
; template <class Epi, bool ALIGN_EPI>
; __device__ __forceinline__ void gemm_phase(LAS unsigned char* lds, const int tid, const Gemm g, const StaticOrder& S, const Epi& E) {
;     ...
;             PG8_LDA(At, 0, 1); PG8_STAGE(PG8_SB(0, 0), b2, voffB); PG8_STAGE(PG8_SB(0, 1), b2 + hstepB, voffB); PG8_STAGE(PG8_SA(0, 0), a2, voffA);
;             PG8_WAIT_V(8); PG8_WAIT_L(0); PG8_BAR; PG8_MMA(1, 0, At, B0); PG8_MMA(1, 1, At, B1); PG8_BAR; PG8_SCHED;
;             PG8_LDB(B0, 1, 0); PG8_LDB(B1, 1, 1); PG8_SCHED; PG8_LDA(At, 1, 0); PG8_STAGE(PG8_SA(0, 1), a2 + hstepA, voffA);
;             PG8_WAIT_V(8); PG8_WAIT_L(0); PG8_BAR; PG8_MMA(0, 0, At, B0); PG8_MMA(0, 1, At, B1); PG8_BAR; PG8_SCHED;
	v_mfma_f32_16x16x32_bf16 v[62:65], v[148:151], v[180:183], v[62:65]
	v_mfma_f32_16x16x32_bf16 v[58:61], v[156:159], v[180:183], v[58:61]
	v_mfma_f32_16x16x32_bf16 v[46:49], v[148:151], v[188:191], v[46:49]
	v_mfma_f32_16x16x32_bf16 v[42:45], v[156:159], v[188:191], v[42:45]
	v_mfma_f32_16x16x32_bf16 v[30:33], v[148:151], v[210:213], v[30:33]
	v_mfma_f32_16x16x32_bf16 v[26:29], v[156:159], v[210:213], v[26:29]
	v_mfma_f32_16x16x32_bf16 v[14:17], v[148:151], v[218:221], v[14:17]
	v_mfma_f32_16x16x32_bf16 v[10:13], v[156:159], v[218:221], v[10:13]
	v_mfma_f32_16x16x32_bf16 v[62:65], v[152:155], v[184:187], v[62:65]
	v_mfma_f32_16x16x32_bf16 v[58:61], v[160:163], v[184:187], v[58:61]
	v_mfma_f32_16x16x32_bf16 v[46:49], v[152:155], v[192:195], v[46:49]
	v_mfma_f32_16x16x32_bf16 v[42:45], v[160:163], v[192:195], v[42:45]
	v_mfma_f32_16x16x32_bf16 v[30:33], v[152:155], v[214:217], v[30:33]
	v_mfma_f32_16x16x32_bf16 v[26:29], v[160:163], v[214:217], v[26:29]
	v_mfma_f32_16x16x32_bf16 v[14:17], v[152:155], v[222:225], v[14:17]
	v_mfma_f32_16x16x32_bf16 v[10:13], v[160:163], v[222:225], v[10:13]
	v_mfma_f32_16x16x32_bf16 v[54:57], v[164:167], v[180:183], v[54:57]
	v_mfma_f32_16x16x32_bf16 v[50:53], v[172:175], v[180:183], v[50:53]
	v_mfma_f32_16x16x32_bf16 v[38:41], v[164:167], v[188:191], v[38:41]
	v_mfma_f32_16x16x32_bf16 v[34:37], v[172:175], v[188:191], v[34:37]
	v_mfma_f32_16x16x32_bf16 v[22:25], v[164:167], v[210:213], v[22:25]
	v_mfma_f32_16x16x32_bf16 v[18:21], v[172:175], v[210:213], v[18:21]
	v_mfma_f32_16x16x32_bf16 v[6:9], v[164:167], v[218:221], v[6:9]
	v_mfma_f32_16x16x32_bf16 v[2:5], v[172:175], v[218:221], v[2:5]
	v_mfma_f32_16x16x32_bf16 v[54:57], v[168:171], v[184:187], v[54:57]
	v_mfma_f32_16x16x32_bf16 v[50:53], v[176:179], v[184:187], v[50:53]
	v_mfma_f32_16x16x32_bf16 v[38:41], v[168:171], v[192:195], v[38:41]
	v_mfma_f32_16x16x32_bf16 v[34:37], v[176:179], v[192:195], v[34:37]
	v_mfma_f32_16x16x32_bf16 v[22:25], v[168:171], v[214:217], v[22:25]
	v_mfma_f32_16x16x32_bf16 v[18:21], v[176:179], v[214:217], v[18:21]
	v_mfma_f32_16x16x32_bf16 v[6:9], v[168:171], v[222:225], v[6:9]
	v_mfma_f32_16x16x32_bf16 v[2:5], v[176:179], v[222:225], v[2:5]
	s_barrier
	s_add_i32 s68, 0, 0x18000
	v_add_u32_e32 v147, s68, v145
	s_add_i32 s69, 0, 0x1c000
	ds_read_b128 v[148:151], v147
	ds_read_b128 v[152:155], v147 offset:1024
	ds_read_b128 v[156:159], v147 offset:2048
	ds_read_b128 v[160:163], v147 offset:3072
	v_add_u32_e32 v147, s69, v145
	ds_read_b128 v[164:167], v147
	ds_read_b128 v[168:171], v147 offset:1024
	ds_read_b128 v[172:175], v147 offset:2048
	ds_read_b128 v[176:179], v147 offset:3072
	s_mov_b32 m0, s23
	s_nop 0
	global_load_lds_dwordx4 v[242:243], off
	s_mov_b32 m0, s52
	s_nop 0
	global_load_lds_dwordx4 v[244:245], off
	s_add_u32 s28, s28, 0x80000
	s_addc_u32 s29, s29, 0
	s_mov_b32 m0, s54
	v_lshl_add_u64 v[246:247], s[28:29], 0, v[134:135]
	ds_read_b128 v[180:183], v146 offset:32768
	ds_read_b128 v[184:187], v146 offset:33792
	ds_read_b128 v[188:191], v146 offset:34816
	ds_read_b128 v[192:195], v146 offset:35840
	ds_read_b128 v[210:213], v146 offset:36864
	ds_read_b128 v[214:217], v146 offset:37888
	ds_read_b128 v[218:221], v146 offset:38912
	ds_read_b128 v[222:225], v146 offset:39936
	global_load_lds_dwordx4 v[246:247], off
	v_lshl_add_u64 v[246:247], s[28:29], 0, v[132:133]
	s_mov_b32 m0, s55
	s_nop 0
	global_load_lds_dwordx4 v[246:247], off
	s_waitcnt vmcnt(8)
	s_waitcnt lgkmcnt(0)
	s_barrier
; #define PG8_STAGE(bufoff, gbase, voff) do { _Pragma("unroll") for (int _i = 0; _i < 2; ++_i) \
;         __builtin_amdgcn_global_load_lds((const unsigned*)((const char*)(gbase) + (voff)[_i]), (LAS unsigned*)(lds + (bufoff) + ldsw + _i * 8192), 16, 0, 0); } while (0)
; #define PG8_LDA(dst, b, h) do { _Pragma("unroll") for (int m = 0; m < 4; ++m) _Pragma("unroll") for (int k = 0; k < 2; ++k) dst[m][k] = *(const LAS bf16x8*)(lds + PG8_SA(b, h) + aoff + m * 2048 + k * 1024); } while (0)
; #define PG8_LDB(dst, b, h) do { _Pragma("unroll") for (int n = 0; n < 2; ++n) _Pragma("unroll") for (int k = 0; k < 2; ++k) dst[n][k] = *(const LAS bf16x8*)(lds + PG8_SB(b, h) + boff + n * 2048 + k * 1024); } while (0)
; #define PG8_MMA(ai, bj, At, Bt) do { __builtin_amdgcn_s_setprio(1); _Pragma("unroll") for (int m = 0; m < 4; ++m) _Pragma("unroll") for (int n = 0; n < 2; ++n) _Pragma("unroll") for (int k = 0; k < 2; ++k) \
;         acc[ai][bj][m][n] = __builtin_amdgcn_mfma_f32_16x16x32_bf16(Bt[n][k], At[m][k], acc[ai][bj][m][n], 0, 0, 0); __builtin_amdgcn_s_setprio(0); } while (0)
; #define PG8_WAIT_V(n) asm volatile("s_waitcnt vmcnt(" #n ")" ::: "memory")
; #define PG8_WAIT_L(n) asm volatile("s_waitcnt lgkmcnt(" #n ")" ::: "memory")
; #define PG8_BAR __builtin_amdgcn_s_barrier()
; #define PG8_SCHED __builtin_amdgcn_sched_barrier(0)
; template <class Epi, bool ALIGN_EPI>
; __device__ __forceinline__ void gemm_phase(LAS unsigned char* lds, const int tid, const Gemm g, const StaticOrder& S, const Epi& E) {
;     ...
;             PG8_LDB(B0, 1, 0); PG8_LDB(B1, 1, 1); PG8_SCHED; PG8_LDA(At, 1, 0); PG8_STAGE(PG8_SA(0, 1), a2 + hstepA, voffA);
;             PG8_WAIT_V(8); PG8_WAIT_L(0); PG8_BAR; PG8_MMA(0, 0, At, B0); PG8_MMA(0, 1, At, B1); PG8_BAR; PG8_SCHED;
;             PG8_LDA(At, 1, 1); PG8_STAGE(PG8_SB(1, 0), b3, voffB); PG8_STAGE(PG8_SB(1, 1), b3 + hstepB, voffB); PG8_STAGE(PG8_SA(1, 0), a3, voffA);
;             PG8_WAIT_V(8); PG8_WAIT_L(0); PG8_BAR; PG8_MMA(1, 0, At, B0); PG8_MMA(1, 1, At, B1); PG8_BAR; PG8_SCHED;
;         }
	v_mfma_f32_16x16x32_bf16 v[126:129], v[148:151], v[180:183], v[126:129]
	v_mfma_f32_16x16x32_bf16 v[122:125], v[156:159], v[180:183], v[122:125]
	v_mfma_f32_16x16x32_bf16 v[110:113], v[148:151], v[188:191], v[110:113]
	v_mfma_f32_16x16x32_bf16 v[106:109], v[156:159], v[188:191], v[106:109]
	v_mfma_f32_16x16x32_bf16 v[94:97], v[148:151], v[210:213], v[94:97]
	v_mfma_f32_16x16x32_bf16 v[90:93], v[156:159], v[210:213], v[90:93]
	v_mfma_f32_16x16x32_bf16 v[78:81], v[148:151], v[218:221], v[78:81]
	v_mfma_f32_16x16x32_bf16 v[74:77], v[156:159], v[218:221], v[74:77]
	v_mfma_f32_16x16x32_bf16 v[126:129], v[152:155], v[184:187], v[126:129]
	v_mfma_f32_16x16x32_bf16 v[122:125], v[160:163], v[184:187], v[122:125]
	v_mfma_f32_16x16x32_bf16 v[110:113], v[152:155], v[192:195], v[110:113]
	v_mfma_f32_16x16x32_bf16 v[106:109], v[160:163], v[192:195], v[106:109]
	v_mfma_f32_16x16x32_bf16 v[94:97], v[152:155], v[214:217], v[94:97]
	v_mfma_f32_16x16x32_bf16 v[90:93], v[160:163], v[214:217], v[90:93]
	v_mfma_f32_16x16x32_bf16 v[78:81], v[152:155], v[222:225], v[78:81]
	v_mfma_f32_16x16x32_bf16 v[74:77], v[160:163], v[222:225], v[74:77]
	v_mfma_f32_16x16x32_bf16 v[118:121], v[164:167], v[180:183], v[118:121]
	v_mfma_f32_16x16x32_bf16 v[114:117], v[172:175], v[180:183], v[114:117]
	v_mfma_f32_16x16x32_bf16 v[102:105], v[164:167], v[188:191], v[102:105]
	v_mfma_f32_16x16x32_bf16 v[98:101], v[172:175], v[188:191], v[98:101]
	v_mfma_f32_16x16x32_bf16 v[86:89], v[164:167], v[210:213], v[86:89]
	v_mfma_f32_16x16x32_bf16 v[82:85], v[172:175], v[210:213], v[82:85]
	v_mfma_f32_16x16x32_bf16 v[70:73], v[164:167], v[218:221], v[70:73]
	v_mfma_f32_16x16x32_bf16 v[66:69], v[172:175], v[218:221], v[66:69]
	v_mfma_f32_16x16x32_bf16 v[118:121], v[168:171], v[184:187], v[118:121]
	v_mfma_f32_16x16x32_bf16 v[114:117], v[176:179], v[184:187], v[114:117]
	v_mfma_f32_16x16x32_bf16 v[102:105], v[168:171], v[192:195], v[102:105]
	v_mfma_f32_16x16x32_bf16 v[98:101], v[176:179], v[192:195], v[98:101]
	v_mfma_f32_16x16x32_bf16 v[86:89], v[168:171], v[214:217], v[86:89]
	v_mfma_f32_16x16x32_bf16 v[82:85], v[176:179], v[214:217], v[82:85]
	v_mfma_f32_16x16x32_bf16 v[70:73], v[168:171], v[222:225], v[70:73]
	v_mfma_f32_16x16x32_bf16 v[66:69], v[176:179], v[222:225], v[66:69]
	s_barrier
	s_add_i32 s28, s68, s30
	v_lshl_add_u64 v[142:143], v[142:143], 0, s[42:43]
	s_mov_b32 m0, s28
	ds_read_b128 v[180:183], v146 offset:49152
	ds_read_b128 v[184:187], v146 offset:50176
	ds_read_b128 v[188:191], v146 offset:51200
	ds_read_b128 v[192:195], v146 offset:52224
	ds_read_b128 v[210:213], v146 offset:53248
	ds_read_b128 v[214:217], v146 offset:54272
	ds_read_b128 v[218:221], v146 offset:55296
	ds_read_b128 v[222:225], v146 offset:56320
	global_load_lds_dwordx4 v[142:143], off
	s_add_i32 m0, s28, 0x2000
	s_add_u32 s26, s26, 0x80080
	v_lshl_add_u64 v[142:143], v[240:241], 0, s[42:43]
	s_addc_u32 s27, s27, 0
	s_add_i32 s28, s69, s30
	global_load_lds_dwordx4 v[142:143], off
	v_lshl_add_u64 v[142:143], s[26:27], 0, v[0:1]
	s_mov_b32 m0, s28
	s_nop 0
	global_load_lds_dwordx4 v[142:143], off
	v_lshl_add_u64 v[142:143], s[26:27], 0, v[130:131]
	s_add_i32 m0, s28, 0x2000
	s_nop 0
	global_load_lds_dwordx4 v[142:143], off
	s_waitcnt vmcnt(4)
	s_waitcnt lgkmcnt(0)
	s_barrier
	v_mfma_f32_16x16x32_bf16 v[62:65], v[148:151], v[180:183], v[62:65]
	v_mfma_f32_16x16x32_bf16 v[58:61], v[156:159], v[180:183], v[58:61]
	v_mfma_f32_16x16x32_bf16 v[46:49], v[148:151], v[188:191], v[46:49]
	v_mfma_f32_16x16x32_bf16 v[42:45], v[156:159], v[188:191], v[42:45]
	v_mfma_f32_16x16x32_bf16 v[30:33], v[148:151], v[210:213], v[30:33]
	v_mfma_f32_16x16x32_bf16 v[26:29], v[156:159], v[210:213], v[26:29]
	v_mfma_f32_16x16x32_bf16 v[14:17], v[148:151], v[218:221], v[14:17]
	v_mfma_f32_16x16x32_bf16 v[10:13], v[156:159], v[218:221], v[10:13]
	v_mfma_f32_16x16x32_bf16 v[62:65], v[152:155], v[184:187], v[62:65]
	v_mfma_f32_16x16x32_bf16 v[58:61], v[160:163], v[184:187], v[58:61]
	v_mfma_f32_16x16x32_bf16 v[46:49], v[152:155], v[192:195], v[46:49]
	v_mfma_f32_16x16x32_bf16 v[42:45], v[160:163], v[192:195], v[42:45]
	v_mfma_f32_16x16x32_bf16 v[30:33], v[152:155], v[214:217], v[30:33]
	v_mfma_f32_16x16x32_bf16 v[26:29], v[160:163], v[214:217], v[26:29]
	v_mfma_f32_16x16x32_bf16 v[14:17], v[152:155], v[222:225], v[14:17]
	v_mfma_f32_16x16x32_bf16 v[10:13], v[160:163], v[222:225], v[10:13]
	v_mfma_f32_16x16x32_bf16 v[54:57], v[164:167], v[180:183], v[54:57]
	v_mfma_f32_16x16x32_bf16 v[50:53], v[172:175], v[180:183], v[50:53]
	v_mfma_f32_16x16x32_bf16 v[38:41], v[164:167], v[188:191], v[38:41]
	v_mfma_f32_16x16x32_bf16 v[34:37], v[172:175], v[188:191], v[34:37]
	v_mfma_f32_16x16x32_bf16 v[22:25], v[164:167], v[210:213], v[22:25]
	v_mfma_f32_16x16x32_bf16 v[18:21], v[172:175], v[210:213], v[18:21]
	v_mfma_f32_16x16x32_bf16 v[6:9], v[164:167], v[218:221], v[6:9]
	v_mfma_f32_16x16x32_bf16 v[2:5], v[172:175], v[218:221], v[2:5]
	v_mfma_f32_16x16x32_bf16 v[54:57], v[168:171], v[184:187], v[54:57]
	v_mfma_f32_16x16x32_bf16 v[50:53], v[176:179], v[184:187], v[50:53]
	v_mfma_f32_16x16x32_bf16 v[38:41], v[168:171], v[192:195], v[38:41]
	v_mfma_f32_16x16x32_bf16 v[34:37], v[176:179], v[192:195], v[34:37]
	v_mfma_f32_16x16x32_bf16 v[22:25], v[168:171], v[214:217], v[22:25]
	v_mfma_f32_16x16x32_bf16 v[18:21], v[176:179], v[214:217], v[18:21]
	v_mfma_f32_16x16x32_bf16 v[6:9], v[168:171], v[222:225], v[6:9]
	v_mfma_f32_16x16x32_bf16 v[2:5], v[176:179], v[222:225], v[2:5]
	s_barrier
	s_add_i32 s67, s67, 2
	s_add_u32 s15, s15, 0x100
	s_addc_u32 s17, s17, 0
	s_add_u32 s24, s24, 0x100
	s_addc_u32 s25, s25, 0
	s_cmp_gt_u32 s67, 29
	s_cbranch_scc0 .LBB0_143
	s_and_b64 vcc, exec, s[12:13]
	s_cbranch_vccz .LBB0_146
	s_barrier

; #define PG8_STAGE(bufoff, gbase, voff) do { _Pragma("unroll") for (int _i = 0; _i < 2; ++_i) \
;         __builtin_amdgcn_global_load_lds((const unsigned*)((const char*)(gbase) + (voff)[_i]), (LAS unsigned*)(lds + (bufoff) + ldsw + _i * 8192), 16, 0, 0); } while (0)
; #define PG8_LDA(dst, b, h) do { _Pragma("unroll") for (int m = 0; m < 4; ++m) _Pragma("unroll") for (int k = 0; k < 2; ++k) dst[m][k] = *(const LAS bf16x8*)(lds + PG8_SA(b, h) + aoff + m * 2048 + k * 1024); } while (0)
; #define PG8_LDB(dst, b, h) do { _Pragma("unroll") for (int n = 0; n < 2; ++n) _Pragma("unroll") for (int k = 0; k < 2; ++k) dst[n][k] = *(const LAS bf16x8*)(lds + PG8_SB(b, h) + boff + n * 2048 + k * 1024); } while (0)
; #define PG8_MMA(ai, bj, At, Bt) do { __builtin_amdgcn_s_setprio(1); _Pragma("unroll") for (int m = 0; m < 4; ++m) _Pragma("unroll") for (int n = 0; n < 2; ++n) _Pragma("unroll") for (int k = 0; k < 2; ++k) \
;         acc[ai][bj][m][n] = __builtin_amdgcn_mfma_f32_16x16x32_bf16(Bt[n][k], At[m][k], acc[ai][bj][m][n], 0, 0, 0); __builtin_amdgcn_s_setprio(0); } while (0)
; #define PG8_WAIT_V(n) asm volatile("s_waitcnt vmcnt(" #n ")" ::: "memory")
; #define PG8_WAIT_L(n) asm volatile("s_waitcnt lgkmcnt(" #n ")" ::: "memory")
; #define PG8_BAR __builtin_amdgcn_s_barrier()
; #define PG8_SCHED __builtin_amdgcn_sched_barrier(0)
; template <class Epi, bool ALIGN_EPI>
; __device__ __forceinline__ void gemm_phase(LAS unsigned char* lds, const int tid, const Gemm g, const StaticOrder& S, const Epi& E) {
;     ...
;             const bool last = (t == nt - 2);
;             const char* a1 = cA + (size_t)(t + 1) * kstepA;
;             const char* a2 = last ? nA : cA + (size_t)(t + 2) * kstepA; const char* b2 = last ? nB : cB + (size_t)(t + 2) * kstepB;
;             const char* a3 = a2 + kstepA; const char* b3 = b2 + kstepB;
;             PG8_LDB(B0, 0, 0); PG8_LDB(B1, 0, 1); PG8_SCHED; PG8_LDA(At, 0, 0); PG8_STAGE(PG8_SA(1, 1), a1 + hstepA, voffA);
;             PG8_WAIT_V(8); PG8_WAIT_L(0); PG8_BAR; PG8_MMA(0, 0, At, B0); PG8_MMA(0, 1, At, B1); PG8_BAR; PG8_SCHED;
;             PG8_LDA(At, 0, 1); PG8_STAGE(PG8_SB(0, 0), b2, voffB); PG8_STAGE(PG8_SB(0, 1), b2 + hstepB, voffB); PG8_STAGE(PG8_SA(0, 0), a2, voffA);
;             PG8_WAIT_V(8); PG8_WAIT_L(0); PG8_BAR; PG8_MMA(1, 0, At, B0); PG8_MMA(1, 1, At, B1); PG8_BAR; PG8_SCHED;
.LBB0_209:
	s_add_i32 s72, s34, 2
	s_add_u32 s35, s30, 0xfff80080
	s_addc_u32 s54, s31, -1
	s_cmp_eq_u32 s21, s34
	s_cselect_b32 s55, s23, s54
	s_cselect_b32 s54, s22, s35
	s_cselect_b32 s35, s25, s71
	s_cselect_b32 s34, s24, s27
	s_add_i32 s73, 0, 0x10000
	s_add_i32 s85, 0, 0x14000
	v_add_u32_e32 v148, s73, v175
	v_add_u32_e32 v164, s85, v175
	ds_read_b128 v[136:139], v148
	ds_read_b128 v[140:143], v148 offset:1024
	ds_read_b128 v[144:147], v148 offset:2048
	ds_read_b128 v[148:151], v148 offset:3072
	ds_read_b128 v[152:155], v164
	ds_read_b128 v[156:159], v164 offset:1024
	ds_read_b128 v[160:163], v164 offset:2048
	ds_read_b128 v[164:167], v164 offset:3072
	v_lshl_add_u64 v[172:173], s[30:31], 0, v[134:135]
	s_add_i32 m0, s58, 0xc000
	ds_read_b128 v[168:171], v177
	ds_read_b128 v[178:181], v177 offset:1024
	ds_read_b128 v[182:185], v177 offset:2048
	ds_read_b128 v[186:189], v177 offset:3072
	ds_read_b128 v[190:193], v177 offset:4096
	ds_read_b128 v[210:213], v177 offset:5120
	ds_read_b128 v[214:217], v177 offset:6144
	ds_read_b128 v[218:221], v177 offset:7168
	global_load_lds_dwordx4 v[172:173], off
	v_lshl_add_u64 v[172:173], s[30:31], 0, v[132:133]
	s_add_i32 m0, s58, 0xe000
	s_nop 0
	global_load_lds_dwordx4 v[172:173], off
	s_sub_u32 s98, s30, 0x80000
	s_subb_u32 s99, s31, 0
	v_lshl_add_u64 v[172:173], s[98:99], 0, v[134:135]
	s_mov_b32 m0, s65
	s_nop 0
	global_load_lds_dwordx4 v[172:173], off
	v_lshl_add_u64 v[172:173], s[98:99], 0, v[132:133]
	s_mov_b32 m0, s66
	s_nop 0
	global_load_lds_dwordx4 v[172:173], off
	s_waitcnt vmcnt(8)
	s_waitcnt lgkmcnt(0)
	s_barrier
	v_mfma_f32_16x16x32_bf16 v[126:129], v[136:139], v[168:171], v[126:129]
	v_mfma_f32_16x16x32_bf16 v[94:97], v[144:147], v[168:171], v[94:97]
	v_mfma_f32_16x16x32_bf16 v[122:125], v[136:139], v[182:185], v[122:125]
	v_mfma_f32_16x16x32_bf16 v[90:93], v[144:147], v[182:185], v[90:93]
	v_mfma_f32_16x16x32_bf16 v[118:121], v[136:139], v[190:193], v[118:121]
	v_mfma_f32_16x16x32_bf16 v[86:89], v[144:147], v[190:193], v[86:89]
	v_mfma_f32_16x16x32_bf16 v[114:117], v[136:139], v[214:217], v[114:117]
	v_mfma_f32_16x16x32_bf16 v[82:85], v[144:147], v[214:217], v[82:85]
	v_mfma_f32_16x16x32_bf16 v[126:129], v[140:143], v[178:181], v[126:129]
	v_mfma_f32_16x16x32_bf16 v[94:97], v[148:151], v[178:181], v[94:97]
	v_mfma_f32_16x16x32_bf16 v[122:125], v[140:143], v[186:189], v[122:125]
	v_mfma_f32_16x16x32_bf16 v[90:93], v[148:151], v[186:189], v[90:93]
	v_mfma_f32_16x16x32_bf16 v[118:121], v[140:143], v[210:213], v[118:121]
	v_mfma_f32_16x16x32_bf16 v[86:89], v[148:151], v[210:213], v[86:89]
	v_mfma_f32_16x16x32_bf16 v[114:117], v[140:143], v[218:221], v[114:117]
	v_mfma_f32_16x16x32_bf16 v[82:85], v[148:151], v[218:221], v[82:85]
	v_mfma_f32_16x16x32_bf16 v[62:65], v[152:155], v[168:171], v[62:65]
	v_mfma_f32_16x16x32_bf16 v[42:45], v[160:163], v[168:171], v[42:45]
	v_mfma_f32_16x16x32_bf16 v[58:61], v[152:155], v[182:185], v[58:61]
	v_mfma_f32_16x16x32_bf16 v[34:37], v[160:163], v[182:185], v[34:37]
	v_mfma_f32_16x16x32_bf16 v[54:57], v[152:155], v[190:193], v[54:57]
	v_mfma_f32_16x16x32_bf16 v[26:29], v[160:163], v[190:193], v[26:29]
	v_mfma_f32_16x16x32_bf16 v[50:53], v[152:155], v[214:217], v[50:53]
	v_mfma_f32_16x16x32_bf16 v[18:21], v[160:163], v[214:217], v[18:21]
	v_mfma_f32_16x16x32_bf16 v[62:65], v[156:159], v[178:181], v[62:65]
	v_mfma_f32_16x16x32_bf16 v[42:45], v[164:167], v[178:181], v[42:45]
	v_mfma_f32_16x16x32_bf16 v[58:61], v[156:159], v[186:189], v[58:61]
	v_mfma_f32_16x16x32_bf16 v[34:37], v[164:167], v[186:189], v[34:37]
	v_mfma_f32_16x16x32_bf16 v[54:57], v[156:159], v[210:213], v[54:57]
	v_mfma_f32_16x16x32_bf16 v[26:29], v[164:167], v[210:213], v[26:29]
	v_mfma_f32_16x16x32_bf16 v[50:53], v[156:159], v[218:221], v[50:53]
	v_mfma_f32_16x16x32_bf16 v[18:21], v[164:167], v[218:221], v[18:21]
	s_barrier
	s_add_i32 s73, s73, s56
	v_lshl_add_u64 v[172:173], s[34:35], 0, v[0:1]
	s_mov_b32 m0, s73
	ds_read_b128 v[168:171], v177 offset:16384
	ds_read_b128 v[178:181], v177 offset:17408
	ds_read_b128 v[182:185], v177 offset:18432
	ds_read_b128 v[186:189], v177 offset:19456
	ds_read_b128 v[190:193], v177 offset:20480
	ds_read_b128 v[210:213], v177 offset:21504
	ds_read_b128 v[214:217], v177 offset:22528
	ds_read_b128 v[218:221], v177 offset:23552
	global_load_lds_dwordx4 v[172:173], off
	s_add_i32 m0, s73, 0x2000
	s_add_u32 s90, s34, 0x80000
	v_lshl_add_u64 v[194:195], s[34:35], 0, v[130:131]
	s_addc_u32 s91, s35, 0
	s_add_i32 s73, s85, s56
	global_load_lds_dwordx4 v[194:195], off
	v_lshl_add_u64 v[222:223], s[90:91], 0, v[0:1]
	s_mov_b32 m0, s73
	v_lshl_add_u64 v[224:225], s[54:55], 0, v[130:131]
	global_load_lds_dwordx4 v[222:223], off
	v_lshl_add_u64 v[222:223], s[90:91], 0, v[130:131]
	s_add_i32 m0, s73, 0x2000
	s_nop 0
	global_load_lds_dwordx4 v[222:223], off
	v_lshl_add_u64 v[222:223], s[54:55], 0, v[0:1]
	s_waitcnt vmcnt(4)
	s_waitcnt lgkmcnt(0)
	s_barrier
; #define PG8_STAGE(bufoff, gbase, voff) do { _Pragma("unroll") for (int _i = 0; _i < 2; ++_i) \
;         __builtin_amdgcn_global_load_lds((const unsigned*)((const char*)(gbase) + (voff)[_i]), (LAS unsigned*)(lds + (bufoff) + ldsw + _i * 8192), 16, 0, 0); } while (0)
; #define PG8_LDA(dst, b, h) do { _Pragma("unroll") for (int m = 0; m < 4; ++m) _Pragma("unroll") for (int k = 0; k < 2; ++k) dst[m][k] = *(const LAS bf16x8*)(lds + PG8_SA(b, h) + aoff + m * 2048 + k * 1024); } while (0)
; #define PG8_LDB(dst, b, h) do { _Pragma("unroll") for (int n = 0; n < 2; ++n) _Pragma("unroll") for (int k = 0; k < 2; ++k) dst[n][k] = *(const LAS bf16x8*)(lds + PG8_SB(b, h) + boff + n * 2048 + k * 1024); } while (0)
; #define PG8_MMA(ai, bj, At, Bt) do { __builtin_amdgcn_s_setprio(1); _Pragma("unroll") for (int m = 0; m < 4; ++m) _Pragma("unroll") for (int n = 0; n < 2; ++n) _Pragma("unroll") for (int k = 0; k < 2; ++k) \
;         acc[ai][bj][m][n] = __builtin_amdgcn_mfma_f32_16x16x32_bf16(Bt[n][k], At[m][k], acc[ai][bj][m][n], 0, 0, 0); __builtin_amdgcn_s_setprio(0); } while (0)
; #define PG8_WAIT_V(n) asm volatile("s_waitcnt vmcnt(" #n ")" ::: "memory")
; #define PG8_WAIT_L(n) asm volatile("s_waitcnt lgkmcnt(" #n ")" ::: "memory")
; #define PG8_BAR __builtin_amdgcn_s_barrier()
; #define PG8_SCHED __builtin_amdgcn_sched_barrier(0)
; template <class Epi, bool ALIGN_EPI>
; __device__ __forceinline__ void gemm_phase(LAS unsigned char* lds, const int tid, const Gemm g, const StaticOrder& S, const Epi& E) {
;     ...
;             PG8_LDA(At, 0, 1); PG8_STAGE(PG8_SB(0, 0), b2, voffB); PG8_STAGE(PG8_SB(0, 1), b2 + hstepB, voffB); PG8_STAGE(PG8_SA(0, 0), a2, voffA);
;             PG8_WAIT_V(8); PG8_WAIT_L(0); PG8_BAR; PG8_MMA(1, 0, At, B0); PG8_MMA(1, 1, At, B1); PG8_BAR; PG8_SCHED;
;             PG8_LDB(B0, 1, 0); PG8_LDB(B1, 1, 1); PG8_SCHED; PG8_LDA(At, 1, 0); PG8_STAGE(PG8_SA(0, 1), a2 + hstepA, voffA);
;             PG8_WAIT_V(8); PG8_WAIT_L(0); PG8_BAR; PG8_MMA(0, 0, At, B0); PG8_MMA(0, 1, At, B1); PG8_BAR; PG8_SCHED;
	v_mfma_f32_16x16x32_bf16 v[110:113], v[136:139], v[168:171], v[110:113]
	v_mfma_f32_16x16x32_bf16 v[78:81], v[144:147], v[168:171], v[78:81]
	v_mfma_f32_16x16x32_bf16 v[106:109], v[136:139], v[182:185], v[106:109]
	v_mfma_f32_16x16x32_bf16 v[74:77], v[144:147], v[182:185], v[74:77]
	v_mfma_f32_16x16x32_bf16 v[102:105], v[136:139], v[190:193], v[102:105]
	v_mfma_f32_16x16x32_bf16 v[70:73], v[144:147], v[190:193], v[70:73]
	v_mfma_f32_16x16x32_bf16 v[98:101], v[136:139], v[214:217], v[98:101]
	v_mfma_f32_16x16x32_bf16 v[66:69], v[144:147], v[214:217], v[66:69]
	v_mfma_f32_16x16x32_bf16 v[110:113], v[140:143], v[178:181], v[110:113]
	v_mfma_f32_16x16x32_bf16 v[78:81], v[148:151], v[178:181], v[78:81]
	v_mfma_f32_16x16x32_bf16 v[106:109], v[140:143], v[186:189], v[106:109]
	v_mfma_f32_16x16x32_bf16 v[74:77], v[148:151], v[186:189], v[74:77]
	v_mfma_f32_16x16x32_bf16 v[102:105], v[140:143], v[210:213], v[102:105]
	v_mfma_f32_16x16x32_bf16 v[70:73], v[148:151], v[210:213], v[70:73]
	v_mfma_f32_16x16x32_bf16 v[98:101], v[140:143], v[218:221], v[98:101]
	v_mfma_f32_16x16x32_bf16 v[66:69], v[148:151], v[218:221], v[66:69]
	v_mfma_f32_16x16x32_bf16 v[46:49], v[152:155], v[168:171], v[46:49]
	v_mfma_f32_16x16x32_bf16 v[14:17], v[160:163], v[168:171], v[14:17]
	v_mfma_f32_16x16x32_bf16 v[38:41], v[152:155], v[182:185], v[38:41]
	v_mfma_f32_16x16x32_bf16 v[10:13], v[160:163], v[182:185], v[10:13]
	v_mfma_f32_16x16x32_bf16 v[30:33], v[152:155], v[190:193], v[30:33]
	v_mfma_f32_16x16x32_bf16 v[6:9], v[160:163], v[190:193], v[6:9]
	v_mfma_f32_16x16x32_bf16 v[22:25], v[152:155], v[214:217], v[22:25]
	v_mfma_f32_16x16x32_bf16 v[2:5], v[160:163], v[214:217], v[2:5]
	v_mfma_f32_16x16x32_bf16 v[46:49], v[156:159], v[178:181], v[46:49]
	v_mfma_f32_16x16x32_bf16 v[14:17], v[164:167], v[178:181], v[14:17]
	v_mfma_f32_16x16x32_bf16 v[38:41], v[156:159], v[186:189], v[38:41]
	v_mfma_f32_16x16x32_bf16 v[10:13], v[164:167], v[186:189], v[10:13]
	v_mfma_f32_16x16x32_bf16 v[30:33], v[156:159], v[210:213], v[30:33]
	v_mfma_f32_16x16x32_bf16 v[6:9], v[164:167], v[210:213], v[6:9]
	v_mfma_f32_16x16x32_bf16 v[22:25], v[156:159], v[218:221], v[22:25]
	v_mfma_f32_16x16x32_bf16 v[2:5], v[164:167], v[218:221], v[2:5]
	s_barrier
	s_add_i32 s73, 0, 0x18000
	s_add_i32 s85, 0, 0x1c000
	v_add_u32_e32 v148, s73, v175
	v_add_u32_e32 v164, s85, v175
	ds_read_b128 v[136:139], v148
	ds_read_b128 v[140:143], v148 offset:1024
	ds_read_b128 v[144:147], v148 offset:2048
	ds_read_b128 v[148:151], v148 offset:3072
	ds_read_b128 v[152:155], v164
	ds_read_b128 v[156:159], v164 offset:1024
	ds_read_b128 v[160:163], v164 offset:2048
	ds_read_b128 v[164:167], v164 offset:3072
	s_mov_b32 m0, s58
	s_nop 0
	global_load_lds_dwordx4 v[222:223], off
	s_mov_b32 m0, s60
	s_nop 0
	global_load_lds_dwordx4 v[224:225], off
	s_add_u32 s54, s54, 0x80000
	s_addc_u32 s55, s55, 0
	s_mov_b32 m0, s61
	v_lshl_add_u64 v[240:241], s[54:55], 0, v[0:1]
	ds_read_b128 v[168:171], v177 offset:32768
	ds_read_b128 v[178:181], v177 offset:33792
	ds_read_b128 v[182:185], v177 offset:34816
	ds_read_b128 v[186:189], v177 offset:35840
	ds_read_b128 v[190:193], v177 offset:36864
	ds_read_b128 v[210:213], v177 offset:37888
	ds_read_b128 v[214:217], v177 offset:38912
	ds_read_b128 v[218:221], v177 offset:39936
	global_load_lds_dwordx4 v[240:241], off
	v_lshl_add_u64 v[240:241], s[54:55], 0, v[130:131]
	s_mov_b32 m0, s62
	s_nop 0
	global_load_lds_dwordx4 v[240:241], off
	s_waitcnt vmcnt(8)
	s_waitcnt lgkmcnt(0)
	s_barrier
; #define PG8_STAGE(bufoff, gbase, voff) do { _Pragma("unroll") for (int _i = 0; _i < 2; ++_i) \
;         __builtin_amdgcn_global_load_lds((const unsigned*)((const char*)(gbase) + (voff)[_i]), (LAS unsigned*)(lds + (bufoff) + ldsw + _i * 8192), 16, 0, 0); } while (0)
; #define PG8_LDA(dst, b, h) do { _Pragma("unroll") for (int m = 0; m < 4; ++m) _Pragma("unroll") for (int k = 0; k < 2; ++k) dst[m][k] = *(const LAS bf16x8*)(lds + PG8_SA(b, h) + aoff + m * 2048 + k * 1024); } while (0)
; #define PG8_LDB(dst, b, h) do { _Pragma("unroll") for (int n = 0; n < 2; ++n) _Pragma("unroll") for (int k = 0; k < 2; ++k) dst[n][k] = *(const LAS bf16x8*)(lds + PG8_SB(b, h) + boff + n * 2048 + k * 1024); } while (0)
; #define PG8_MMA(ai, bj, At, Bt) do { __builtin_amdgcn_s_setprio(1); _Pragma("unroll") for (int m = 0; m < 4; ++m) _Pragma("unroll") for (int n = 0; n < 2; ++n) _Pragma("unroll") for (int k = 0; k < 2; ++k) \
;         acc[ai][bj][m][n] = __builtin_amdgcn_mfma_f32_16x16x32_bf16(Bt[n][k], At[m][k], acc[ai][bj][m][n], 0, 0, 0); __builtin_amdgcn_s_setprio(0); } while (0)
; #define PG8_WAIT_V(n) asm volatile("s_waitcnt vmcnt(" #n ")" ::: "memory")
; #define PG8_WAIT_L(n) asm volatile("s_waitcnt lgkmcnt(" #n ")" ::: "memory")
; #define PG8_BAR __builtin_amdgcn_s_barrier()
; #define PG8_SCHED __builtin_amdgcn_sched_barrier(0)
; template <class Epi, bool ALIGN_EPI>
; __device__ __forceinline__ void gemm_phase(LAS unsigned char* lds, const int tid, const Gemm g, const StaticOrder& S, const Epi& E) {
;     ...
;             PG8_LDB(B0, 1, 0); PG8_LDB(B1, 1, 1); PG8_SCHED; PG8_LDA(At, 1, 0); PG8_STAGE(PG8_SA(0, 1), a2 + hstepA, voffA);
;             PG8_WAIT_V(8); PG8_WAIT_L(0); PG8_BAR; PG8_MMA(0, 0, At, B0); PG8_MMA(0, 1, At, B1); PG8_BAR; PG8_SCHED;
;             PG8_LDA(At, 1, 1); PG8_STAGE(PG8_SB(1, 0), b3, voffB); PG8_STAGE(PG8_SB(1, 1), b3 + hstepB, voffB); PG8_STAGE(PG8_SA(1, 0), a3, voffA);
;             PG8_WAIT_V(8); PG8_WAIT_L(0); PG8_BAR; PG8_MMA(1, 0, At, B0); PG8_MMA(1, 1, At, B1); PG8_BAR; PG8_SCHED;
;         }
	v_mfma_f32_16x16x32_bf16 v[126:129], v[136:139], v[168:171], v[126:129]
	v_mfma_f32_16x16x32_bf16 v[94:97], v[144:147], v[168:171], v[94:97]
	v_mfma_f32_16x16x32_bf16 v[122:125], v[136:139], v[182:185], v[122:125]
	v_mfma_f32_16x16x32_bf16 v[90:93], v[144:147], v[182:185], v[90:93]
	v_mfma_f32_16x16x32_bf16 v[118:121], v[136:139], v[190:193], v[118:121]
	v_mfma_f32_16x16x32_bf16 v[86:89], v[144:147], v[190:193], v[86:89]
	v_mfma_f32_16x16x32_bf16 v[114:117], v[136:139], v[214:217], v[114:117]
	v_mfma_f32_16x16x32_bf16 v[82:85], v[144:147], v[214:217], v[82:85]
	v_mfma_f32_16x16x32_bf16 v[126:129], v[140:143], v[178:181], v[126:129]
	v_mfma_f32_16x16x32_bf16 v[94:97], v[148:151], v[178:181], v[94:97]
	v_mfma_f32_16x16x32_bf16 v[122:125], v[140:143], v[186:189], v[122:125]
	v_mfma_f32_16x16x32_bf16 v[90:93], v[148:151], v[186:189], v[90:93]
	v_mfma_f32_16x16x32_bf16 v[118:121], v[140:143], v[210:213], v[118:121]
	v_mfma_f32_16x16x32_bf16 v[86:89], v[148:151], v[210:213], v[86:89]
	v_mfma_f32_16x16x32_bf16 v[114:117], v[140:143], v[218:221], v[114:117]
	v_mfma_f32_16x16x32_bf16 v[82:85], v[148:151], v[218:221], v[82:85]
	v_mfma_f32_16x16x32_bf16 v[62:65], v[152:155], v[168:171], v[62:65]
	v_mfma_f32_16x16x32_bf16 v[42:45], v[160:163], v[168:171], v[42:45]
	v_mfma_f32_16x16x32_bf16 v[58:61], v[152:155], v[182:185], v[58:61]
	v_mfma_f32_16x16x32_bf16 v[34:37], v[160:163], v[182:185], v[34:37]
	v_mfma_f32_16x16x32_bf16 v[54:57], v[152:155], v[190:193], v[54:57]
	v_mfma_f32_16x16x32_bf16 v[26:29], v[160:163], v[190:193], v[26:29]
	v_mfma_f32_16x16x32_bf16 v[50:53], v[152:155], v[214:217], v[50:53]
	v_mfma_f32_16x16x32_bf16 v[18:21], v[160:163], v[214:217], v[18:21]
	v_mfma_f32_16x16x32_bf16 v[62:65], v[156:159], v[178:181], v[62:65]
	v_mfma_f32_16x16x32_bf16 v[42:45], v[164:167], v[178:181], v[42:45]
	v_mfma_f32_16x16x32_bf16 v[58:61], v[156:159], v[186:189], v[58:61]
	v_mfma_f32_16x16x32_bf16 v[34:37], v[164:167], v[186:189], v[34:37]
	v_mfma_f32_16x16x32_bf16 v[54:57], v[156:159], v[210:213], v[54:57]
	v_mfma_f32_16x16x32_bf16 v[26:29], v[164:167], v[210:213], v[26:29]
	v_mfma_f32_16x16x32_bf16 v[50:53], v[156:159], v[218:221], v[50:53]
	v_mfma_f32_16x16x32_bf16 v[18:21], v[164:167], v[218:221], v[18:21]
	s_barrier
	s_add_i32 s54, s73, s56
	v_lshl_add_u64 v[172:173], v[172:173], 0, s[42:43]
	s_mov_b32 m0, s54
	ds_read_b128 v[168:171], v177 offset:49152
	ds_read_b128 v[178:181], v177 offset:50176
	ds_read_b128 v[182:185], v177 offset:51200
	ds_read_b128 v[186:189], v177 offset:52224
	ds_read_b128 v[190:193], v177 offset:53248
	ds_read_b128 v[210:213], v177 offset:54272
	ds_read_b128 v[214:217], v177 offset:55296
	ds_read_b128 v[218:221], v177 offset:56320
	global_load_lds_dwordx4 v[172:173], off
	s_add_i32 m0, s54, 0x2000
	s_add_u32 s34, s34, 0x80080
	v_lshl_add_u64 v[172:173], v[194:195], 0, s[42:43]
	s_addc_u32 s35, s35, 0
	s_add_i32 s54, s85, s56
	global_load_lds_dwordx4 v[172:173], off
	v_lshl_add_u64 v[172:173], s[34:35], 0, v[0:1]
	s_mov_b32 m0, s54
	s_nop 0
	global_load_lds_dwordx4 v[172:173], off
	v_lshl_add_u64 v[172:173], s[34:35], 0, v[130:131]
	s_add_i32 m0, s54, 0x2000
	s_nop 0
	global_load_lds_dwordx4 v[172:173], off
	s_waitcnt vmcnt(4)
	s_waitcnt lgkmcnt(0)
	s_barrier
	v_mfma_f32_16x16x32_bf16 v[110:113], v[136:139], v[168:171], v[110:113]
	v_mfma_f32_16x16x32_bf16 v[78:81], v[144:147], v[168:171], v[78:81]
	v_mfma_f32_16x16x32_bf16 v[106:109], v[136:139], v[182:185], v[106:109]
	v_mfma_f32_16x16x32_bf16 v[74:77], v[144:147], v[182:185], v[74:77]
	v_mfma_f32_16x16x32_bf16 v[102:105], v[136:139], v[190:193], v[102:105]
	v_mfma_f32_16x16x32_bf16 v[70:73], v[144:147], v[190:193], v[70:73]
	v_mfma_f32_16x16x32_bf16 v[98:101], v[136:139], v[214:217], v[98:101]
	v_mfma_f32_16x16x32_bf16 v[66:69], v[144:147], v[214:217], v[66:69]
	v_mfma_f32_16x16x32_bf16 v[110:113], v[140:143], v[178:181], v[110:113]
	v_mfma_f32_16x16x32_bf16 v[78:81], v[148:151], v[178:181], v[78:81]
	v_mfma_f32_16x16x32_bf16 v[106:109], v[140:143], v[186:189], v[106:109]
	v_mfma_f32_16x16x32_bf16 v[74:77], v[148:151], v[186:189], v[74:77]
	v_mfma_f32_16x16x32_bf16 v[102:105], v[140:143], v[210:213], v[102:105]
	v_mfma_f32_16x16x32_bf16 v[70:73], v[148:151], v[210:213], v[70:73]
	v_mfma_f32_16x16x32_bf16 v[98:101], v[140:143], v[218:221], v[98:101]
	v_mfma_f32_16x16x32_bf16 v[66:69], v[148:151], v[218:221], v[66:69]
	v_mfma_f32_16x16x32_bf16 v[46:49], v[152:155], v[168:171], v[46:49]
	v_mfma_f32_16x16x32_bf16 v[14:17], v[160:163], v[168:171], v[14:17]
	v_mfma_f32_16x16x32_bf16 v[38:41], v[152:155], v[182:185], v[38:41]
	v_mfma_f32_16x16x32_bf16 v[10:13], v[160:163], v[182:185], v[10:13]
	v_mfma_f32_16x16x32_bf16 v[30:33], v[152:155], v[190:193], v[30:33]
	v_mfma_f32_16x16x32_bf16 v[6:9], v[160:163], v[190:193], v[6:9]
	v_mfma_f32_16x16x32_bf16 v[22:25], v[152:155], v[214:217], v[22:25]
	v_mfma_f32_16x16x32_bf16 v[2:5], v[160:163], v[214:217], v[2:5]
	v_mfma_f32_16x16x32_bf16 v[46:49], v[156:159], v[178:181], v[46:49]
	v_mfma_f32_16x16x32_bf16 v[14:17], v[164:167], v[178:181], v[14:17]
	v_mfma_f32_16x16x32_bf16 v[38:41], v[156:159], v[186:189], v[38:41]
	v_mfma_f32_16x16x32_bf16 v[10:13], v[164:167], v[186:189], v[10:13]
	v_mfma_f32_16x16x32_bf16 v[30:33], v[156:159], v[210:213], v[30:33]
	v_mfma_f32_16x16x32_bf16 v[6:9], v[164:167], v[210:213], v[6:9]
	v_mfma_f32_16x16x32_bf16 v[22:25], v[156:159], v[218:221], v[22:25]
	v_mfma_f32_16x16x32_bf16 v[2:5], v[164:167], v[218:221], v[2:5]
	s_barrier
	s_add_u32 s27, s27, 0x100
	s_addc_u32 s71, s71, 0
	s_add_u32 s30, s30, 0x100
	s_addc_u32 s31, s31, 0
	s_cmp_ge_u32 s72, s19
	s_mov_b32 s34, s72
	s_cbranch_scc0 .LBB0_209
	s_and_b64 vcc, exec, s[16:17]
	s_cbranch_vccz .LBB0_212
	s_barrier

; #define PG8_STAGE(bufoff, gbase, voff) do { _Pragma("unroll") for (int _i = 0; _i < 2; ++_i) \
;         __builtin_amdgcn_global_load_lds((const unsigned*)((const char*)(gbase) + (voff)[_i]), (LAS unsigned*)(lds + (bufoff) + ldsw + _i * 8192), 16, 0, 0); } while (0)
; #define PG8_LDA(dst, b, h) do { _Pragma("unroll") for (int m = 0; m < 4; ++m) _Pragma("unroll") for (int k = 0; k < 2; ++k) dst[m][k] = *(const LAS bf16x8*)(lds + PG8_SA(b, h) + aoff + m * 2048 + k * 1024); } while (0)
; #define PG8_LDB(dst, b, h) do { _Pragma("unroll") for (int n = 0; n < 2; ++n) _Pragma("unroll") for (int k = 0; k < 2; ++k) dst[n][k] = *(const LAS bf16x8*)(lds + PG8_SB(b, h) + boff + n * 2048 + k * 1024); } while (0)
; #define PG8_MMA(ai, bj, At, Bt) do { __builtin_amdgcn_s_setprio(1); _Pragma("unroll") for (int m = 0; m < 4; ++m) _Pragma("unroll") for (int n = 0; n < 2; ++n) _Pragma("unroll") for (int k = 0; k < 2; ++k) \
;         acc[ai][bj][m][n] = __builtin_amdgcn_mfma_f32_16x16x32_bf16(Bt[n][k], At[m][k], acc[ai][bj][m][n], 0, 0, 0); __builtin_amdgcn_s_setprio(0); } while (0)
; #define PG8_WAIT_V(n) asm volatile("s_waitcnt vmcnt(" #n ")" ::: "memory")
; #define PG8_WAIT_L(n) asm volatile("s_waitcnt lgkmcnt(" #n ")" ::: "memory")
; #define PG8_BAR __builtin_amdgcn_s_barrier()
; #define PG8_SCHED __builtin_amdgcn_sched_barrier(0)
; template <class Epi, bool ALIGN_EPI>
; __device__ __forceinline__ void gemm_phase(LAS unsigned char* lds, const int tid, const Gemm g, const StaticOrder& S, const Epi& E) {
;     ...
;             const bool last = (t == nt - 2);
;             const char* a1 = cA + (size_t)(t + 1) * kstepA;
;             const char* a2 = last ? nA : cA + (size_t)(t + 2) * kstepA; const char* b2 = last ? nB : cB + (size_t)(t + 2) * kstepB;
;             const char* a3 = a2 + kstepA; const char* b3 = b2 + kstepB;
;             PG8_LDB(B0, 0, 0); PG8_LDB(B1, 0, 1); PG8_SCHED; PG8_LDA(At, 0, 0); PG8_STAGE(PG8_SA(1, 1), a1 + hstepA, voffA);
;             PG8_WAIT_V(8); PG8_WAIT_L(0); PG8_BAR; PG8_MMA(0, 0, At, B0); PG8_MMA(0, 1, At, B1); PG8_BAR; PG8_SCHED;
;             PG8_LDA(At, 0, 1); PG8_STAGE(PG8_SB(0, 0), b2, voffB); PG8_STAGE(PG8_SB(0, 1), b2 + hstepB, voffB); PG8_STAGE(PG8_SA(0, 0), a2, voffA);
;             PG8_WAIT_V(8); PG8_WAIT_L(0); PG8_BAR; PG8_MMA(1, 0, At, B0); PG8_MMA(1, 1, At, B1); PG8_BAR; PG8_SCHED;
.LBB0_263:
	s_add_i32 s5, s5, 2
	s_add_u32 s34, s30, 0xfff80080
	s_addc_u32 s35, s31, -1
	s_add_i32 s94, 0, 0x10000
	s_cmp_eq_u32 s91, s92
	s_cselect_b32 s55, s23, s35
	s_cselect_b32 s54, s22, s34
	v_add_u32_e32 v0, s94, v205
	s_cselect_b32 s35, s25, s36
	s_cselect_b32 s34, s24, s21
	s_add_i32 s96, 0, 0x14000
	ds_read_b128 v[132:135], v0
	ds_read_b128 v[136:139], v0 offset:1024
	ds_read_b128 v[140:143], v0 offset:2048
	ds_read_b128 v[144:147], v0 offset:3072
	v_add_u32_e32 v0, s96, v205
	ds_read_b128 v[148:151], v0
	ds_read_b128 v[152:155], v0 offset:1024
	ds_read_b128 v[156:159], v0 offset:2048
	ds_read_b128 v[160:163], v0 offset:3072
	v_lshl_add_u64 v[2:3], s[30:31], 0, v[220:221]
	s_add_i32 m0, s68, 0xc000
	ds_read_b128 v[164:167], v209
	ds_read_b128 v[168:171], v209 offset:1024
	ds_read_b128 v[172:175], v209 offset:2048
	ds_read_b128 v[176:179], v209 offset:3072
	ds_read_b128 v[180:183], v209 offset:4096
	ds_read_b128 v[184:187], v209 offset:5120
	ds_read_b128 v[188:191], v209 offset:6144
	ds_read_b128 v[192:195], v209 offset:7168
	global_load_lds_dwordx4 v[2:3], off
	v_lshl_add_u64 v[2:3], s[30:31], 0, v[218:219]
	s_add_i32 m0, s68, 0xe000
	s_nop 0
	global_load_lds_dwordx4 v[2:3], off
	s_sub_u32 s98, s30, 0x80000
	s_subb_u32 s99, s31, 0
	v_lshl_add_u64 v[2:3], s[98:99], 0, v[220:221]
	s_mov_b32 m0, s72
	s_nop 0
	global_load_lds_dwordx4 v[2:3], off
	v_lshl_add_u64 v[2:3], s[98:99], 0, v[218:219]
	s_mov_b32 m0, s73
	s_nop 0
	global_load_lds_dwordx4 v[2:3], off
	s_waitcnt vmcnt(8)
	s_waitcnt lgkmcnt(0)
	s_barrier
	v_mfma_f32_16x16x32_bf16 v[128:131], v[132:135], v[164:167], v[128:131]
	v_mfma_f32_16x16x32_bf16 v[124:127], v[140:143], v[164:167], v[124:127]
	v_mfma_f32_16x16x32_bf16 v[112:115], v[132:135], v[172:175], v[112:115]
	v_mfma_f32_16x16x32_bf16 v[108:111], v[140:143], v[172:175], v[108:111]
	v_mfma_f32_16x16x32_bf16 v[96:99], v[132:135], v[180:183], v[96:99]
	v_mfma_f32_16x16x32_bf16 v[92:95], v[140:143], v[180:183], v[92:95]
	v_mfma_f32_16x16x32_bf16 v[80:83], v[132:135], v[188:191], v[80:83]
	v_mfma_f32_16x16x32_bf16 v[76:79], v[140:143], v[188:191], v[76:79]
	v_mfma_f32_16x16x32_bf16 v[128:131], v[136:139], v[168:171], v[128:131]
	v_mfma_f32_16x16x32_bf16 v[124:127], v[144:147], v[168:171], v[124:127]
	v_mfma_f32_16x16x32_bf16 v[112:115], v[136:139], v[176:179], v[112:115]
	v_mfma_f32_16x16x32_bf16 v[108:111], v[144:147], v[176:179], v[108:111]
	v_mfma_f32_16x16x32_bf16 v[96:99], v[136:139], v[184:187], v[96:99]
	v_mfma_f32_16x16x32_bf16 v[92:95], v[144:147], v[184:187], v[92:95]
	v_mfma_f32_16x16x32_bf16 v[80:83], v[136:139], v[192:195], v[80:83]
	v_mfma_f32_16x16x32_bf16 v[76:79], v[144:147], v[192:195], v[76:79]
	v_mfma_f32_16x16x32_bf16 v[120:123], v[148:151], v[164:167], v[120:123]
	v_mfma_f32_16x16x32_bf16 v[116:119], v[156:159], v[164:167], v[116:119]
	v_mfma_f32_16x16x32_bf16 v[104:107], v[148:151], v[172:175], v[104:107]
	v_mfma_f32_16x16x32_bf16 v[100:103], v[156:159], v[172:175], v[100:103]
	v_mfma_f32_16x16x32_bf16 v[88:91], v[148:151], v[180:183], v[88:91]
	v_mfma_f32_16x16x32_bf16 v[84:87], v[156:159], v[180:183], v[84:87]
	v_mfma_f32_16x16x32_bf16 v[72:75], v[148:151], v[188:191], v[72:75]
	v_mfma_f32_16x16x32_bf16 v[68:71], v[156:159], v[188:191], v[68:71]
	v_mfma_f32_16x16x32_bf16 v[120:123], v[152:155], v[168:171], v[120:123]
	v_mfma_f32_16x16x32_bf16 v[116:119], v[160:163], v[168:171], v[116:119]
	v_mfma_f32_16x16x32_bf16 v[104:107], v[152:155], v[176:179], v[104:107]
	v_mfma_f32_16x16x32_bf16 v[100:103], v[160:163], v[176:179], v[100:103]
	v_mfma_f32_16x16x32_bf16 v[88:91], v[152:155], v[184:187], v[88:91]
	v_mfma_f32_16x16x32_bf16 v[84:87], v[160:163], v[184:187], v[84:87]
	v_mfma_f32_16x16x32_bf16 v[72:75], v[152:155], v[192:195], v[72:75]
	v_mfma_f32_16x16x32_bf16 v[68:71], v[160:163], v[192:195], v[68:71]
	s_barrier
	s_add_i32 s94, s94, s67
	v_lshl_add_u64 v[240:241], s[34:35], 0, v[212:213]
	s_mov_b32 m0, s94
	ds_read_b128 v[164:167], v209 offset:16384
	ds_read_b128 v[168:171], v209 offset:17408
	ds_read_b128 v[172:175], v209 offset:18432
	ds_read_b128 v[176:179], v209 offset:19456
	ds_read_b128 v[180:183], v209 offset:20480
	ds_read_b128 v[184:187], v209 offset:21504
	ds_read_b128 v[188:191], v209 offset:22528
	ds_read_b128 v[192:195], v209 offset:23552
	global_load_lds_dwordx4 v[240:241], off
	s_add_i32 m0, s94, 0x2000
	s_add_u32 s94, s34, 0x80000
	v_lshl_add_u64 v[242:243], s[34:35], 0, v[216:217]
	s_addc_u32 s95, s35, 0
	s_add_i32 s96, s96, s67
	global_load_lds_dwordx4 v[242:243], off
	v_lshl_add_u64 v[2:3], s[94:95], 0, v[212:213]
	s_mov_b32 m0, s96
	v_lshl_add_u64 v[244:245], s[54:55], 0, v[210:211]
	global_load_lds_dwordx4 v[2:3], off
	v_lshl_add_u64 v[2:3], s[94:95], 0, v[216:217]
	s_add_i32 m0, s96, 0x2000
	v_lshl_add_u64 v[246:247], s[54:55], 0, v[214:215]
	global_load_lds_dwordx4 v[2:3], off
	s_waitcnt vmcnt(4)
	s_waitcnt lgkmcnt(0)
	s_barrier
; #define PG8_STAGE(bufoff, gbase, voff) do { _Pragma("unroll") for (int _i = 0; _i < 2; ++_i) \
;         __builtin_amdgcn_global_load_lds((const unsigned*)((const char*)(gbase) + (voff)[_i]), (LAS unsigned*)(lds + (bufoff) + ldsw + _i * 8192), 16, 0, 0); } while (0)
; #define PG8_LDA(dst, b, h) do { _Pragma("unroll") for (int m = 0; m < 4; ++m) _Pragma("unroll") for (int k = 0; k < 2; ++k) dst[m][k] = *(const LAS bf16x8*)(lds + PG8_SA(b, h) + aoff + m * 2048 + k * 1024); } while (0)
; #define PG8_LDB(dst, b, h) do { _Pragma("unroll") for (int n = 0; n < 2; ++n) _Pragma("unroll") for (int k = 0; k < 2; ++k) dst[n][k] = *(const LAS bf16x8*)(lds + PG8_SB(b, h) + boff + n * 2048 + k * 1024); } while (0)
; #define PG8_MMA(ai, bj, At, Bt) do { __builtin_amdgcn_s_setprio(1); _Pragma("unroll") for (int m = 0; m < 4; ++m) _Pragma("unroll") for (int n = 0; n < 2; ++n) _Pragma("unroll") for (int k = 0; k < 2; ++k) \
;         acc[ai][bj][m][n] = __builtin_amdgcn_mfma_f32_16x16x32_bf16(Bt[n][k], At[m][k], acc[ai][bj][m][n], 0, 0, 0); __builtin_amdgcn_s_setprio(0); } while (0)
; #define PG8_WAIT_V(n) asm volatile("s_waitcnt vmcnt(" #n ")" ::: "memory")
; #define PG8_WAIT_L(n) asm volatile("s_waitcnt lgkmcnt(" #n ")" ::: "memory")
; #define PG8_BAR __builtin_amdgcn_s_barrier()
; #define PG8_SCHED __builtin_amdgcn_sched_barrier(0)
; template <class Epi, bool ALIGN_EPI>
; __device__ __forceinline__ void gemm_phase(LAS unsigned char* lds, const int tid, const Gemm g, const StaticOrder& S, const Epi& E) {
;     ...
;             PG8_WAIT_V(8); PG8_WAIT_L(0); PG8_BAR; PG8_MMA(1, 0, At, B0); PG8_MMA(1, 1, At, B1); PG8_BAR; PG8_SCHED;
;             PG8_LDB(B0, 1, 0); PG8_LDB(B1, 1, 1); PG8_SCHED; PG8_LDA(At, 1, 0); PG8_STAGE(PG8_SA(0, 1), a2 + hstepA, voffA);
;             PG8_WAIT_V(8); PG8_WAIT_L(0); PG8_BAR; PG8_MMA(0, 0, At, B0); PG8_MMA(0, 1, At, B1); PG8_BAR; PG8_SCHED;
	v_mfma_f32_16x16x32_bf16 v[64:67], v[132:135], v[164:167], v[64:67]
	v_mfma_f32_16x16x32_bf16 v[60:63], v[140:143], v[164:167], v[60:63]
	v_mfma_f32_16x16x32_bf16 v[48:51], v[132:135], v[172:175], v[48:51]
	v_mfma_f32_16x16x32_bf16 v[44:47], v[140:143], v[172:175], v[44:47]
	v_mfma_f32_16x16x32_bf16 v[32:35], v[132:135], v[180:183], v[32:35]
	v_mfma_f32_16x16x32_bf16 v[28:31], v[140:143], v[180:183], v[28:31]
	v_mfma_f32_16x16x32_bf16 v[16:19], v[132:135], v[188:191], v[16:19]
	v_mfma_f32_16x16x32_bf16 v[12:15], v[140:143], v[188:191], v[12:15]
	v_mfma_f32_16x16x32_bf16 v[64:67], v[136:139], v[168:171], v[64:67]
	v_mfma_f32_16x16x32_bf16 v[60:63], v[144:147], v[168:171], v[60:63]
	v_mfma_f32_16x16x32_bf16 v[48:51], v[136:139], v[176:179], v[48:51]
	v_mfma_f32_16x16x32_bf16 v[44:47], v[144:147], v[176:179], v[44:47]
	v_mfma_f32_16x16x32_bf16 v[32:35], v[136:139], v[184:187], v[32:35]
	v_mfma_f32_16x16x32_bf16 v[28:31], v[144:147], v[184:187], v[28:31]
	v_mfma_f32_16x16x32_bf16 v[16:19], v[136:139], v[192:195], v[16:19]
	v_mfma_f32_16x16x32_bf16 v[12:15], v[144:147], v[192:195], v[12:15]
	v_mfma_f32_16x16x32_bf16 v[56:59], v[148:151], v[164:167], v[56:59]
	v_mfma_f32_16x16x32_bf16 v[52:55], v[156:159], v[164:167], v[52:55]
	v_mfma_f32_16x16x32_bf16 v[40:43], v[148:151], v[172:175], v[40:43]
	v_mfma_f32_16x16x32_bf16 v[36:39], v[156:159], v[172:175], v[36:39]
	v_mfma_f32_16x16x32_bf16 v[24:27], v[148:151], v[180:183], v[24:27]
	v_mfma_f32_16x16x32_bf16 v[20:23], v[156:159], v[180:183], v[20:23]
	v_mfma_f32_16x16x32_bf16 v[8:11], v[148:151], v[188:191], v[8:11]
	v_mfma_f32_16x16x32_bf16 v[2:5], v[156:159], v[188:191], v[4:7]
	v_mfma_f32_16x16x32_bf16 v[56:59], v[152:155], v[168:171], v[56:59]
	v_mfma_f32_16x16x32_bf16 v[52:55], v[160:163], v[168:171], v[52:55]
	v_mfma_f32_16x16x32_bf16 v[40:43], v[152:155], v[176:179], v[40:43]
	v_mfma_f32_16x16x32_bf16 v[36:39], v[160:163], v[176:179], v[36:39]
	v_mfma_f32_16x16x32_bf16 v[24:27], v[152:155], v[184:187], v[24:27]
	v_mfma_f32_16x16x32_bf16 v[20:23], v[160:163], v[184:187], v[20:23]
	v_mfma_f32_16x16x32_bf16 v[8:11], v[152:155], v[192:195], v[8:11]
	v_mfma_f32_16x16x32_bf16 v[2:5], v[160:163], v[192:195], v[2:5]
	s_barrier
	s_add_i32 s94, 0, 0x18000
	v_add_u32_e32 v0, s94, v205
	s_add_i32 s95, 0, 0x1c000
	ds_read_b128 v[132:135], v0
	ds_read_b128 v[136:139], v0 offset:1024
	ds_read_b128 v[140:143], v0 offset:2048
	ds_read_b128 v[144:147], v0 offset:3072
	v_add_u32_e32 v0, s95, v205
	ds_read_b128 v[148:151], v0
	ds_read_b128 v[152:155], v0 offset:1024
	ds_read_b128 v[156:159], v0 offset:2048
	ds_read_b128 v[160:163], v0 offset:3072
	s_mov_b32 m0, s68
	s_nop 0
	global_load_lds_dwordx4 v[244:245], off
	s_mov_b32 m0, s69
	s_nop 0
	global_load_lds_dwordx4 v[246:247], off
	s_add_u32 s54, s54, 0x80000
	s_addc_u32 s55, s55, 0
	s_mov_b32 m0, s70
	v_lshl_add_u64 v[6:7], s[54:55], 0, v[210:211]
	ds_read_b128 v[164:167], v209 offset:32768
	ds_read_b128 v[168:171], v209 offset:33792
	ds_read_b128 v[172:175], v209 offset:34816
	ds_read_b128 v[176:179], v209 offset:35840
	ds_read_b128 v[180:183], v209 offset:36864
	ds_read_b128 v[184:187], v209 offset:37888
	ds_read_b128 v[188:191], v209 offset:38912
	ds_read_b128 v[192:195], v209 offset:39936
	global_load_lds_dwordx4 v[6:7], off
	v_lshl_add_u64 v[6:7], s[54:55], 0, v[214:215]
	s_mov_b32 m0, s71
	s_nop 0
	global_load_lds_dwordx4 v[6:7], off
	s_waitcnt vmcnt(8)
	s_waitcnt lgkmcnt(0)
	s_barrier
; #define PG8_STAGE(bufoff, gbase, voff) do { _Pragma("unroll") for (int _i = 0; _i < 2; ++_i) \
;         __builtin_amdgcn_global_load_lds((const unsigned*)((const char*)(gbase) + (voff)[_i]), (LAS unsigned*)(lds + (bufoff) + ldsw + _i * 8192), 16, 0, 0); } while (0)
; #define PG8_LDA(dst, b, h) do { _Pragma("unroll") for (int m = 0; m < 4; ++m) _Pragma("unroll") for (int k = 0; k < 2; ++k) dst[m][k] = *(const LAS bf16x8*)(lds + PG8_SA(b, h) + aoff + m * 2048 + k * 1024); } while (0)
; #define PG8_MMA(ai, bj, At, Bt) do { __builtin_amdgcn_s_setprio(1); _Pragma("unroll") for (int m = 0; m < 4; ++m) _Pragma("unroll") for (int n = 0; n < 2; ++n) _Pragma("unroll") for (int k = 0; k < 2; ++k) \
;         acc[ai][bj][m][n] = __builtin_amdgcn_mfma_f32_16x16x32_bf16(Bt[n][k], At[m][k], acc[ai][bj][m][n], 0, 0, 0); __builtin_amdgcn_s_setprio(0); } while (0)
; #define PG8_WAIT_V(n) asm volatile("s_waitcnt vmcnt(" #n ")" ::: "memory")
; #define PG8_WAIT_L(n) asm volatile("s_waitcnt lgkmcnt(" #n ")" ::: "memory")
; #define PG8_BAR __builtin_amdgcn_s_barrier()
; #define PG8_SCHED __builtin_amdgcn_sched_barrier(0)
; template <class Epi, bool ALIGN_EPI>
; __device__ __forceinline__ void gemm_phase(LAS unsigned char* lds, const int tid, const Gemm g, const StaticOrder& S, const Epi& E) {
;     ...
;             PG8_WAIT_V(8); PG8_WAIT_L(0); PG8_BAR; PG8_MMA(0, 0, At, B0); PG8_MMA(0, 1, At, B1); PG8_BAR; PG8_SCHED;
;             PG8_LDA(At, 1, 1); PG8_STAGE(PG8_SB(1, 0), b3, voffB); PG8_STAGE(PG8_SB(1, 1), b3 + hstepB, voffB); PG8_STAGE(PG8_SA(1, 0), a3, voffA);
;             PG8_WAIT_V(8); PG8_WAIT_L(0); PG8_BAR; PG8_MMA(1, 0, At, B0); PG8_MMA(1, 1, At, B1); PG8_BAR; PG8_SCHED;
;         }
	v_mfma_f32_16x16x32_bf16 v[128:131], v[132:135], v[164:167], v[128:131]
	v_mfma_f32_16x16x32_bf16 v[124:127], v[140:143], v[164:167], v[124:127]
	v_mfma_f32_16x16x32_bf16 v[112:115], v[132:135], v[172:175], v[112:115]
	v_mfma_f32_16x16x32_bf16 v[108:111], v[140:143], v[172:175], v[108:111]
	v_mfma_f32_16x16x32_bf16 v[96:99], v[132:135], v[180:183], v[96:99]
	v_mfma_f32_16x16x32_bf16 v[92:95], v[140:143], v[180:183], v[92:95]
	v_mfma_f32_16x16x32_bf16 v[80:83], v[132:135], v[188:191], v[80:83]
	v_mfma_f32_16x16x32_bf16 v[76:79], v[140:143], v[188:191], v[76:79]
	v_mfma_f32_16x16x32_bf16 v[128:131], v[136:139], v[168:171], v[128:131]
	v_mfma_f32_16x16x32_bf16 v[124:127], v[144:147], v[168:171], v[124:127]
	v_mfma_f32_16x16x32_bf16 v[112:115], v[136:139], v[176:179], v[112:115]
	v_mfma_f32_16x16x32_bf16 v[108:111], v[144:147], v[176:179], v[108:111]
	v_mfma_f32_16x16x32_bf16 v[96:99], v[136:139], v[184:187], v[96:99]
	v_mfma_f32_16x16x32_bf16 v[92:95], v[144:147], v[184:187], v[92:95]
	v_mfma_f32_16x16x32_bf16 v[80:83], v[136:139], v[192:195], v[80:83]
	v_mfma_f32_16x16x32_bf16 v[76:79], v[144:147], v[192:195], v[76:79]
	v_mfma_f32_16x16x32_bf16 v[120:123], v[148:151], v[164:167], v[120:123]
	v_mfma_f32_16x16x32_bf16 v[116:119], v[156:159], v[164:167], v[116:119]
	v_mfma_f32_16x16x32_bf16 v[104:107], v[148:151], v[172:175], v[104:107]
	v_mfma_f32_16x16x32_bf16 v[100:103], v[156:159], v[172:175], v[100:103]
	v_mfma_f32_16x16x32_bf16 v[88:91], v[148:151], v[180:183], v[88:91]
	v_mfma_f32_16x16x32_bf16 v[84:87], v[156:159], v[180:183], v[84:87]
	v_mfma_f32_16x16x32_bf16 v[72:75], v[148:151], v[188:191], v[72:75]
	v_mfma_f32_16x16x32_bf16 v[68:71], v[156:159], v[188:191], v[68:71]
	v_mfma_f32_16x16x32_bf16 v[120:123], v[152:155], v[168:171], v[120:123]
	v_mfma_f32_16x16x32_bf16 v[116:119], v[160:163], v[168:171], v[116:119]
	v_mfma_f32_16x16x32_bf16 v[104:107], v[152:155], v[176:179], v[104:107]
	v_mfma_f32_16x16x32_bf16 v[100:103], v[160:163], v[176:179], v[100:103]
	v_mfma_f32_16x16x32_bf16 v[88:91], v[152:155], v[184:187], v[88:91]
	v_mfma_f32_16x16x32_bf16 v[84:87], v[160:163], v[184:187], v[84:87]
	v_mfma_f32_16x16x32_bf16 v[72:75], v[152:155], v[192:195], v[72:75]
	v_mfma_f32_16x16x32_bf16 v[68:71], v[160:163], v[192:195], v[68:71]
	s_barrier
	s_add_i32 s54, s94, s67
	v_lshl_add_u64 v[6:7], v[240:241], 0, s[42:43]
	s_mov_b32 m0, s54
	ds_read_b128 v[164:167], v209 offset:49152
	ds_read_b128 v[168:171], v209 offset:50176
	ds_read_b128 v[172:175], v209 offset:51200
	ds_read_b128 v[176:179], v209 offset:52224
	ds_read_b128 v[180:183], v209 offset:53248
	ds_read_b128 v[184:187], v209 offset:54272
	ds_read_b128 v[188:191], v209 offset:55296
	ds_read_b128 v[192:195], v209 offset:56320
	global_load_lds_dwordx4 v[6:7], off
	s_add_i32 m0, s54, 0x2000
	s_add_u32 s34, s34, 0x80080
	v_lshl_add_u64 v[6:7], v[242:243], 0, s[42:43]
	s_addc_u32 s35, s35, 0
	s_add_i32 s54, s95, s67
	global_load_lds_dwordx4 v[6:7], off
	v_lshl_add_u64 v[6:7], s[34:35], 0, v[212:213]
	s_mov_b32 m0, s54
	s_nop 0
	global_load_lds_dwordx4 v[6:7], off
	v_lshl_add_u64 v[6:7], s[34:35], 0, v[216:217]
	s_add_i32 m0, s54, 0x2000
	s_nop 0
	global_load_lds_dwordx4 v[6:7], off
	s_waitcnt vmcnt(4)
	s_waitcnt lgkmcnt(0)
	s_barrier
	v_mfma_f32_16x16x32_bf16 v[64:67], v[132:135], v[164:167], v[64:67]
	v_mfma_f32_16x16x32_bf16 v[60:63], v[140:143], v[164:167], v[60:63]
	v_mfma_f32_16x16x32_bf16 v[48:51], v[132:135], v[172:175], v[48:51]
	v_mfma_f32_16x16x32_bf16 v[44:47], v[140:143], v[172:175], v[44:47]
	v_mfma_f32_16x16x32_bf16 v[32:35], v[132:135], v[180:183], v[32:35]
	v_mfma_f32_16x16x32_bf16 v[28:31], v[140:143], v[180:183], v[28:31]
	v_mfma_f32_16x16x32_bf16 v[16:19], v[132:135], v[188:191], v[16:19]
	v_mfma_f32_16x16x32_bf16 v[12:15], v[140:143], v[188:191], v[12:15]
	v_mfma_f32_16x16x32_bf16 v[64:67], v[136:139], v[168:171], v[64:67]
	v_mfma_f32_16x16x32_bf16 v[60:63], v[144:147], v[168:171], v[60:63]
	v_mfma_f32_16x16x32_bf16 v[48:51], v[136:139], v[176:179], v[48:51]
	v_mfma_f32_16x16x32_bf16 v[44:47], v[144:147], v[176:179], v[44:47]
	v_mfma_f32_16x16x32_bf16 v[32:35], v[136:139], v[184:187], v[32:35]
	v_mfma_f32_16x16x32_bf16 v[28:31], v[144:147], v[184:187], v[28:31]
	v_mfma_f32_16x16x32_bf16 v[16:19], v[136:139], v[192:195], v[16:19]
	v_mfma_f32_16x16x32_bf16 v[12:15], v[144:147], v[192:195], v[12:15]
	v_mfma_f32_16x16x32_bf16 v[56:59], v[148:151], v[164:167], v[56:59]
	v_mfma_f32_16x16x32_bf16 v[52:55], v[156:159], v[164:167], v[52:55]
	v_mfma_f32_16x16x32_bf16 v[40:43], v[148:151], v[172:175], v[40:43]
	v_mfma_f32_16x16x32_bf16 v[36:39], v[156:159], v[172:175], v[36:39]
	v_mfma_f32_16x16x32_bf16 v[24:27], v[148:151], v[180:183], v[24:27]
	v_mfma_f32_16x16x32_bf16 v[20:23], v[156:159], v[180:183], v[20:23]
	v_mfma_f32_16x16x32_bf16 v[6:9], v[148:151], v[188:191], v[8:11]
	v_mfma_f32_16x16x32_bf16 v[2:5], v[156:159], v[188:191], v[2:5]
	v_mfma_f32_16x16x32_bf16 v[56:59], v[152:155], v[168:171], v[56:59]
	v_mfma_f32_16x16x32_bf16 v[52:55], v[160:163], v[168:171], v[52:55]
	v_mfma_f32_16x16x32_bf16 v[40:43], v[152:155], v[176:179], v[40:43]
	v_mfma_f32_16x16x32_bf16 v[36:39], v[160:163], v[176:179], v[36:39]
	v_mfma_f32_16x16x32_bf16 v[24:27], v[152:155], v[184:187], v[24:27]
	v_mfma_f32_16x16x32_bf16 v[20:23], v[160:163], v[184:187], v[20:23]
	v_mfma_f32_16x16x32_bf16 v[8:11], v[152:155], v[192:195], v[6:9]
	v_mfma_f32_16x16x32_bf16 v[4:7], v[160:163], v[192:195], v[2:5]
	s_barrier
	s_add_u32 s92, s92, 0x400
	s_addc_u32 s93, s93, 0
	s_add_u32 s21, s21, 0x100
	s_addc_u32 s36, s36, 0
	s_add_u32 s30, s30, 0x100
	s_addc_u32 s31, s31, 0
	s_cmp_ge_u32 s5, s19
	s_cbranch_scc1 .LBB0_266

; #define PG8_STAGE(bufoff, gbase, voff) do { _Pragma("unroll") for (int _i = 0; _i < 2; ++_i) \
;         __builtin_amdgcn_global_load_lds((const unsigned*)((const char*)(gbase) + (voff)[_i]), (LAS unsigned*)(lds + (bufoff) + ldsw + _i * 8192), 16, 0, 0); } while (0)
; #define PG8_LDA(dst, b, h) do { _Pragma("unroll") for (int m = 0; m < 4; ++m) _Pragma("unroll") for (int k = 0; k < 2; ++k) dst[m][k] = *(const LAS bf16x8*)(lds + PG8_SA(b, h) + aoff + m * 2048 + k * 1024); } while (0)
; #define PG8_LDB(dst, b, h) do { _Pragma("unroll") for (int n = 0; n < 2; ++n) _Pragma("unroll") for (int k = 0; k < 2; ++k) dst[n][k] = *(const LAS bf16x8*)(lds + PG8_SB(b, h) + boff + n * 2048 + k * 1024); } while (0)
; #define PG8_MMA(ai, bj, At, Bt) do { __builtin_amdgcn_s_setprio(1); _Pragma("unroll") for (int m = 0; m < 4; ++m) _Pragma("unroll") for (int n = 0; n < 2; ++n) _Pragma("unroll") for (int k = 0; k < 2; ++k) \
;         acc[ai][bj][m][n] = __builtin_amdgcn_mfma_f32_16x16x32_bf16(Bt[n][k], At[m][k], acc[ai][bj][m][n], 0, 0, 0); __builtin_amdgcn_s_setprio(0); } while (0)
; #define PG8_WAIT_V(n) asm volatile("s_waitcnt vmcnt(" #n ")" ::: "memory")
; #define PG8_WAIT_L(n) asm volatile("s_waitcnt lgkmcnt(" #n ")" ::: "memory")
; #define PG8_BAR __builtin_amdgcn_s_barrier()
; #define PG8_SCHED __builtin_amdgcn_sched_barrier(0)
; template <class Epi, bool ALIGN_EPI>
; __device__ __forceinline__ void gemm_phase(LAS unsigned char* lds, const int tid, const Gemm g, const StaticOrder& S, const Epi& E) {
;     ...
;             const bool last = (t == nt - 2);
;             const char* a1 = cA + (size_t)(t + 1) * kstepA;
;             const char* a2 = last ? nA : cA + (size_t)(t + 2) * kstepA; const char* b2 = last ? nB : cB + (size_t)(t + 2) * kstepB;
;             const char* a3 = a2 + kstepA; const char* b3 = b2 + kstepB;
;             PG8_LDB(B0, 0, 0); PG8_LDB(B1, 0, 1); PG8_SCHED; PG8_LDA(At, 0, 0); PG8_STAGE(PG8_SA(1, 1), a1 + hstepA, voffA);
;             PG8_WAIT_V(8); PG8_WAIT_L(0); PG8_BAR; PG8_MMA(0, 0, At, B0); PG8_MMA(0, 1, At, B1); PG8_BAR; PG8_SCHED;
;             PG8_LDA(At, 0, 1); PG8_STAGE(PG8_SB(0, 0), b2, voffB); PG8_STAGE(PG8_SB(0, 1), b2 + hstepB, voffB); PG8_STAGE(PG8_SA(0, 0), a2, voffA);
;             PG8_WAIT_V(8); PG8_WAIT_L(0); PG8_BAR; PG8_MMA(1, 0, At, B0); PG8_MMA(1, 1, At, B1); PG8_BAR; PG8_SCHED;
.LBB0_667:
	s_add_u32 s22, s20, 0xfff80080
	s_addc_u32 s23, s21, -1
	s_add_i32 s49, 0, 0x10000
	s_cmp_eq_u32 s19, 28
	s_cselect_b32 s25, s15, s23
	s_cselect_b32 s24, s14, s22
	v_add_u32_e32 v0, s49, v173
	s_cselect_b32 s23, s17, s13
	s_cselect_b32 s22, s16, s11
	s_add_i32 s52, 0, 0x14000
	ds_read_b128 v[130:133], v0
	ds_read_b128 v[134:137], v0 offset:1024
	ds_read_b128 v[138:141], v0 offset:2048
	ds_read_b128 v[142:145], v0 offset:3072
	v_add_u32_e32 v0, s52, v173
	ds_read_b128 v[158:161], v0
	ds_read_b128 v[162:165], v0 offset:1024
	ds_read_b128 v[166:169], v0 offset:2048
	ds_read_b128 v[178:181], v0 offset:3072
	v_lshl_add_u64 v[170:171], s[20:21], 0, v[156:157]
	s_add_i32 m0, s28, 0xc000
	ds_read_b128 v[182:185], v176
	ds_read_b128 v[186:189], v176 offset:1024
	ds_read_b128 v[190:193], v176 offset:2048
	ds_read_b128 v[208:211], v176 offset:3072
	ds_read_b128 v[212:215], v176 offset:4096
	ds_read_b128 v[216:219], v176 offset:5120
	ds_read_b128 v[220:223], v176 offset:6144
	ds_read_b128 v[240:243], v176 offset:7168
	global_load_lds_dwordx4 v[170:171], off
	v_lshl_add_u64 v[170:171], s[20:21], 0, v[154:155]
	s_add_i32 m0, s28, 0xe000
	s_nop 0
	global_load_lds_dwordx4 v[170:171], off
	s_sub_u32 s98, s20, 0x80000
	s_subb_u32 s99, s21, 0
	v_lshl_add_u64 v[170:171], s[98:99], 0, v[156:157]
	s_mov_b32 m0, s34
	s_nop 0
	global_load_lds_dwordx4 v[170:171], off
	v_lshl_add_u64 v[170:171], s[98:99], 0, v[154:155]
	s_mov_b32 m0, s35
	s_nop 0
	global_load_lds_dwordx4 v[170:171], off
	s_waitcnt vmcnt(8)
	s_waitcnt lgkmcnt(0)
	s_barrier
	v_mfma_f32_16x16x32_bf16 v[126:129], v[130:133], v[182:185], v[126:129]
	v_mfma_f32_16x16x32_bf16 v[122:125], v[138:141], v[182:185], v[122:125]
	v_mfma_f32_16x16x32_bf16 v[118:121], v[130:133], v[190:193], v[118:121]
	v_mfma_f32_16x16x32_bf16 v[114:117], v[138:141], v[190:193], v[114:117]
	v_mfma_f32_16x16x32_bf16 v[102:105], v[130:133], v[212:215], v[102:105]
	v_mfma_f32_16x16x32_bf16 v[98:101], v[138:141], v[212:215], v[98:101]
	v_mfma_f32_16x16x32_bf16 v[86:89], v[130:133], v[220:223], v[86:89]
	v_mfma_f32_16x16x32_bf16 v[82:85], v[138:141], v[220:223], v[82:85]
	v_mfma_f32_16x16x32_bf16 v[126:129], v[134:137], v[186:189], v[126:129]
	v_mfma_f32_16x16x32_bf16 v[122:125], v[142:145], v[186:189], v[122:125]
	v_mfma_f32_16x16x32_bf16 v[118:121], v[134:137], v[208:211], v[118:121]
	v_mfma_f32_16x16x32_bf16 v[114:117], v[142:145], v[208:211], v[114:117]
	v_mfma_f32_16x16x32_bf16 v[102:105], v[134:137], v[216:219], v[102:105]
	v_mfma_f32_16x16x32_bf16 v[98:101], v[142:145], v[216:219], v[98:101]
	v_mfma_f32_16x16x32_bf16 v[86:89], v[134:137], v[240:243], v[86:89]
	v_mfma_f32_16x16x32_bf16 v[82:85], v[142:145], v[240:243], v[82:85]
	v_mfma_f32_16x16x32_bf16 v[110:113], v[158:161], v[182:185], v[110:113]
	v_mfma_f32_16x16x32_bf16 v[106:109], v[166:169], v[182:185], v[106:109]
	v_mfma_f32_16x16x32_bf16 v[94:97], v[158:161], v[190:193], v[94:97]
	v_mfma_f32_16x16x32_bf16 v[90:93], v[166:169], v[190:193], v[90:93]
	v_mfma_f32_16x16x32_bf16 v[78:81], v[158:161], v[212:215], v[78:81]
	v_mfma_f32_16x16x32_bf16 v[74:77], v[166:169], v[212:215], v[74:77]
	v_mfma_f32_16x16x32_bf16 v[70:73], v[158:161], v[220:223], v[70:73]
	v_mfma_f32_16x16x32_bf16 v[66:69], v[166:169], v[220:223], v[66:69]
	v_mfma_f32_16x16x32_bf16 v[110:113], v[162:165], v[186:189], v[110:113]
	v_mfma_f32_16x16x32_bf16 v[106:109], v[178:181], v[186:189], v[106:109]
	v_mfma_f32_16x16x32_bf16 v[94:97], v[162:165], v[208:211], v[94:97]
	v_mfma_f32_16x16x32_bf16 v[90:93], v[178:181], v[208:211], v[90:93]
	v_mfma_f32_16x16x32_bf16 v[78:81], v[162:165], v[216:219], v[78:81]
	v_mfma_f32_16x16x32_bf16 v[74:77], v[178:181], v[216:219], v[74:77]
	v_mfma_f32_16x16x32_bf16 v[70:73], v[162:165], v[240:243], v[70:73]
	v_mfma_f32_16x16x32_bf16 v[66:69], v[178:181], v[240:243], v[66:69]
	s_barrier
	s_add_i32 s49, s49, s27
	v_lshl_add_u64 v[170:171], s[22:23], 0, v[148:149]
	s_mov_b32 m0, s49
	ds_read_b128 v[182:185], v176 offset:16384
	ds_read_b128 v[186:189], v176 offset:17408
	ds_read_b128 v[190:193], v176 offset:18432
	ds_read_b128 v[208:211], v176 offset:19456
	ds_read_b128 v[212:215], v176 offset:20480
	ds_read_b128 v[216:219], v176 offset:21504
	ds_read_b128 v[220:223], v176 offset:22528
	ds_read_b128 v[240:243], v176 offset:23552
	global_load_lds_dwordx4 v[170:171], off
	s_add_i32 m0, s49, 0x2000
	s_add_u32 s54, s22, 0x80000
	v_lshl_add_u64 v[194:195], s[22:23], 0, v[152:153]
	s_addc_u32 s55, s23, 0
	s_add_i32 s49, s52, s27
	global_load_lds_dwordx4 v[194:195], off
	v_lshl_add_u64 v[224:225], s[54:55], 0, v[148:149]
	s_mov_b32 m0, s49
	v_lshl_add_u64 v[244:245], s[24:25], 0, v[150:151]
	global_load_lds_dwordx4 v[224:225], off
	v_lshl_add_u64 v[224:225], s[54:55], 0, v[152:153]
	s_add_i32 m0, s49, 0x2000
	s_nop 0
	global_load_lds_dwordx4 v[224:225], off
	v_lshl_add_u64 v[224:225], s[24:25], 0, v[146:147]
	s_waitcnt vmcnt(4)
	s_waitcnt lgkmcnt(0)
	s_barrier
; #define PG8_STAGE(bufoff, gbase, voff) do { _Pragma("unroll") for (int _i = 0; _i < 2; ++_i) \
;         __builtin_amdgcn_global_load_lds((const unsigned*)((const char*)(gbase) + (voff)[_i]), (LAS unsigned*)(lds + (bufoff) + ldsw + _i * 8192), 16, 0, 0); } while (0)
; #define PG8_LDA(dst, b, h) do { _Pragma("unroll") for (int m = 0; m < 4; ++m) _Pragma("unroll") for (int k = 0; k < 2; ++k) dst[m][k] = *(const LAS bf16x8*)(lds + PG8_SA(b, h) + aoff + m * 2048 + k * 1024); } while (0)
; #define PG8_LDB(dst, b, h) do { _Pragma("unroll") for (int n = 0; n < 2; ++n) _Pragma("unroll") for (int k = 0; k < 2; ++k) dst[n][k] = *(const LAS bf16x8*)(lds + PG8_SB(b, h) + boff + n * 2048 + k * 1024); } while (0)
; #define PG8_MMA(ai, bj, At, Bt) do { __builtin_amdgcn_s_setprio(1); _Pragma("unroll") for (int m = 0; m < 4; ++m) _Pragma("unroll") for (int n = 0; n < 2; ++n) _Pragma("unroll") for (int k = 0; k < 2; ++k) \
;         acc[ai][bj][m][n] = __builtin_amdgcn_mfma_f32_16x16x32_bf16(Bt[n][k], At[m][k], acc[ai][bj][m][n], 0, 0, 0); __builtin_amdgcn_s_setprio(0); } while (0)
; #define PG8_WAIT_V(n) asm volatile("s_waitcnt vmcnt(" #n ")" ::: "memory")
; #define PG8_WAIT_L(n) asm volatile("s_waitcnt lgkmcnt(" #n ")" ::: "memory")
; #define PG8_BAR __builtin_amdgcn_s_barrier()
; #define PG8_SCHED __builtin_amdgcn_sched_barrier(0)
; template <class Epi, bool ALIGN_EPI>
; __device__ __forceinline__ void gemm_phase(LAS unsigned char* lds, const int tid, const Gemm g, const StaticOrder& S, const Epi& E) {
;     ...
;             PG8_WAIT_V(8); PG8_WAIT_L(0); PG8_BAR; PG8_MMA(1, 0, At, B0); PG8_MMA(1, 1, At, B1); PG8_BAR; PG8_SCHED;
;             PG8_LDB(B0, 1, 0); PG8_LDB(B1, 1, 1); PG8_SCHED; PG8_LDA(At, 1, 0); PG8_STAGE(PG8_SA(0, 1), a2 + hstepA, voffA);
;             PG8_WAIT_V(8); PG8_WAIT_L(0); PG8_BAR; PG8_MMA(0, 0, At, B0); PG8_MMA(0, 1, At, B1); PG8_BAR; PG8_SCHED;
;             PG8_LDA(At, 1, 1); PG8_STAGE(PG8_SB(1, 0), b3, voffB); PG8_STAGE(PG8_SB(1, 1), b3 + hstepB, voffB); PG8_STAGE(PG8_SA(1, 0), a3, voffA);
;             PG8_WAIT_V(8); PG8_WAIT_L(0); PG8_BAR; PG8_MMA(1, 0, At, B0); PG8_MMA(1, 1, At, B1); PG8_BAR; PG8_SCHED;
	v_mfma_f32_16x16x32_bf16 v[62:65], v[130:133], v[182:185], v[62:65]
	v_mfma_f32_16x16x32_bf16 v[58:61], v[138:141], v[182:185], v[58:61]
	v_mfma_f32_16x16x32_bf16 v[54:57], v[130:133], v[190:193], v[54:57]
	v_mfma_f32_16x16x32_bf16 v[50:53], v[138:141], v[190:193], v[50:53]
	v_mfma_f32_16x16x32_bf16 v[38:41], v[130:133], v[212:215], v[38:41]
	v_mfma_f32_16x16x32_bf16 v[34:37], v[138:141], v[212:215], v[34:37]
	v_mfma_f32_16x16x32_bf16 v[22:25], v[130:133], v[220:223], v[22:25]
	v_mfma_f32_16x16x32_bf16 v[18:21], v[138:141], v[220:223], v[18:21]
	v_mfma_f32_16x16x32_bf16 v[62:65], v[134:137], v[186:189], v[62:65]
	v_mfma_f32_16x16x32_bf16 v[58:61], v[142:145], v[186:189], v[58:61]
	v_mfma_f32_16x16x32_bf16 v[54:57], v[134:137], v[208:211], v[54:57]
	v_mfma_f32_16x16x32_bf16 v[50:53], v[142:145], v[208:211], v[50:53]
	v_mfma_f32_16x16x32_bf16 v[38:41], v[134:137], v[216:219], v[38:41]
	v_mfma_f32_16x16x32_bf16 v[34:37], v[142:145], v[216:219], v[34:37]
	v_mfma_f32_16x16x32_bf16 v[22:25], v[134:137], v[240:243], v[22:25]
	v_mfma_f32_16x16x32_bf16 v[18:21], v[142:145], v[240:243], v[18:21]
	v_mfma_f32_16x16x32_bf16 v[46:49], v[158:161], v[182:185], v[46:49]
	v_mfma_f32_16x16x32_bf16 v[42:45], v[166:169], v[182:185], v[42:45]
	v_mfma_f32_16x16x32_bf16 v[30:33], v[158:161], v[190:193], v[30:33]
	v_mfma_f32_16x16x32_bf16 v[26:29], v[166:169], v[190:193], v[26:29]
	v_mfma_f32_16x16x32_bf16 v[14:17], v[158:161], v[212:215], v[14:17]
	v_mfma_f32_16x16x32_bf16 v[10:13], v[166:169], v[212:215], v[10:13]
	v_mfma_f32_16x16x32_bf16 v[6:9], v[158:161], v[220:223], v[6:9]
	v_mfma_f32_16x16x32_bf16 v[2:5], v[166:169], v[220:223], v[2:5]
	v_mfma_f32_16x16x32_bf16 v[46:49], v[162:165], v[186:189], v[46:49]
	v_mfma_f32_16x16x32_bf16 v[42:45], v[178:181], v[186:189], v[42:45]
	v_mfma_f32_16x16x32_bf16 v[30:33], v[162:165], v[208:211], v[30:33]
	v_mfma_f32_16x16x32_bf16 v[26:29], v[178:181], v[208:211], v[26:29]
	v_mfma_f32_16x16x32_bf16 v[14:17], v[162:165], v[216:219], v[14:17]
	v_mfma_f32_16x16x32_bf16 v[10:13], v[178:181], v[216:219], v[10:13]
	v_mfma_f32_16x16x32_bf16 v[6:9], v[162:165], v[240:243], v[6:9]
	v_mfma_f32_16x16x32_bf16 v[2:5], v[178:181], v[240:243], v[2:5]
	s_barrier
	s_add_i32 s49, 0, 0x18000
	v_add_u32_e32 v0, s49, v173
	s_add_i32 s52, 0, 0x1c000
	ds_read_b128 v[130:133], v0
	ds_read_b128 v[134:137], v0 offset:1024
	ds_read_b128 v[138:141], v0 offset:2048
	ds_read_b128 v[142:145], v0 offset:3072
	v_add_u32_e32 v0, s52, v173
	ds_read_b128 v[158:161], v0
	ds_read_b128 v[162:165], v0 offset:1024
	ds_read_b128 v[166:169], v0 offset:2048
	ds_read_b128 v[178:181], v0 offset:3072
	s_mov_b32 m0, s28
	s_nop 0
	global_load_lds_dwordx4 v[224:225], off
	s_mov_b32 m0, s29
	s_nop 0
	global_load_lds_dwordx4 v[244:245], off
	s_add_u32 s24, s24, 0x80000
	s_addc_u32 s25, s25, 0
	s_mov_b32 m0, s30
	v_lshl_add_u64 v[246:247], s[24:25], 0, v[146:147]
	ds_read_b128 v[182:185], v176 offset:32768
	ds_read_b128 v[186:189], v176 offset:33792
	ds_read_b128 v[190:193], v176 offset:34816
	ds_read_b128 v[208:211], v176 offset:35840
	ds_read_b128 v[212:215], v176 offset:36864
	ds_read_b128 v[216:219], v176 offset:37888
	ds_read_b128 v[220:223], v176 offset:38912
	ds_read_b128 v[240:243], v176 offset:39936
	global_load_lds_dwordx4 v[246:247], off
	v_lshl_add_u64 v[246:247], s[24:25], 0, v[150:151]
	s_mov_b32 m0, s31
	s_nop 0
	global_load_lds_dwordx4 v[246:247], off
	s_waitcnt vmcnt(8)
	s_waitcnt lgkmcnt(0)
	s_barrier
	v_mfma_f32_16x16x32_bf16 v[126:129], v[130:133], v[182:185], v[126:129]
	v_mfma_f32_16x16x32_bf16 v[122:125], v[138:141], v[182:185], v[122:125]
	v_mfma_f32_16x16x32_bf16 v[118:121], v[130:133], v[190:193], v[118:121]
	v_mfma_f32_16x16x32_bf16 v[114:117], v[138:141], v[190:193], v[114:117]
	v_mfma_f32_16x16x32_bf16 v[102:105], v[130:133], v[212:215], v[102:105]
	v_mfma_f32_16x16x32_bf16 v[98:101], v[138:141], v[212:215], v[98:101]
	v_mfma_f32_16x16x32_bf16 v[86:89], v[130:133], v[220:223], v[86:89]
	v_mfma_f32_16x16x32_bf16 v[82:85], v[138:141], v[220:223], v[82:85]
	v_mfma_f32_16x16x32_bf16 v[126:129], v[134:137], v[186:189], v[126:129]
	v_mfma_f32_16x16x32_bf16 v[122:125], v[142:145], v[186:189], v[122:125]
	v_mfma_f32_16x16x32_bf16 v[118:121], v[134:137], v[208:211], v[118:121]
	v_mfma_f32_16x16x32_bf16 v[114:117], v[142:145], v[208:211], v[114:117]
	v_mfma_f32_16x16x32_bf16 v[102:105], v[134:137], v[216:219], v[102:105]
	v_mfma_f32_16x16x32_bf16 v[98:101], v[142:145], v[216:219], v[98:101]
	v_mfma_f32_16x16x32_bf16 v[86:89], v[134:137], v[240:243], v[86:89]
	v_mfma_f32_16x16x32_bf16 v[82:85], v[142:145], v[240:243], v[82:85]
	v_mfma_f32_16x16x32_bf16 v[110:113], v[158:161], v[182:185], v[110:113]
	v_mfma_f32_16x16x32_bf16 v[106:109], v[166:169], v[182:185], v[106:109]
	v_mfma_f32_16x16x32_bf16 v[94:97], v[158:161], v[190:193], v[94:97]
	v_mfma_f32_16x16x32_bf16 v[90:93], v[166:169], v[190:193], v[90:93]
	v_mfma_f32_16x16x32_bf16 v[78:81], v[158:161], v[212:215], v[78:81]
	v_mfma_f32_16x16x32_bf16 v[74:77], v[166:169], v[212:215], v[74:77]
	v_mfma_f32_16x16x32_bf16 v[70:73], v[158:161], v[220:223], v[70:73]
	v_mfma_f32_16x16x32_bf16 v[66:69], v[166:169], v[220:223], v[66:69]
	v_mfma_f32_16x16x32_bf16 v[110:113], v[162:165], v[186:189], v[110:113]
	v_mfma_f32_16x16x32_bf16 v[106:109], v[178:181], v[186:189], v[106:109]
	v_mfma_f32_16x16x32_bf16 v[94:97], v[162:165], v[208:211], v[94:97]
	v_mfma_f32_16x16x32_bf16 v[90:93], v[178:181], v[208:211], v[90:93]
	v_mfma_f32_16x16x32_bf16 v[78:81], v[162:165], v[216:219], v[78:81]
	v_mfma_f32_16x16x32_bf16 v[74:77], v[178:181], v[216:219], v[74:77]
	v_mfma_f32_16x16x32_bf16 v[70:73], v[162:165], v[240:243], v[70:73]
	v_mfma_f32_16x16x32_bf16 v[66:69], v[178:181], v[240:243], v[66:69]
	s_barrier
; #define GAS __attribute__((address_space(1)))
; #define PG8_STAGE(bufoff, gbase, voff) do { _Pragma("unroll") for (int _i = 0; _i < 2; ++_i) \
;         __builtin_amdgcn_global_load_lds((const unsigned*)((const char*)(gbase) + (voff)[_i]), (LAS unsigned*)(lds + (bufoff) + ldsw + _i * 8192), 16, 0, 0); } while (0)
; #define PG8_LDA(dst, b, h) do { _Pragma("unroll") for (int m = 0; m < 4; ++m) _Pragma("unroll") for (int k = 0; k < 2; ++k) dst[m][k] = *(const LAS bf16x8*)(lds + PG8_SA(b, h) + aoff + m * 2048 + k * 1024); } while (0)
; #define PG8_MMA(ai, bj, At, Bt) do { __builtin_amdgcn_s_setprio(1); _Pragma("unroll") for (int m = 0; m < 4; ++m) _Pragma("unroll") for (int n = 0; n < 2; ++n) _Pragma("unroll") for (int k = 0; k < 2; ++k) \
;         acc[ai][bj][m][n] = __builtin_amdgcn_mfma_f32_16x16x32_bf16(Bt[n][k], At[m][k], acc[ai][bj][m][n], 0, 0, 0); __builtin_amdgcn_s_setprio(0); } while (0)
; #define PG8_WAIT_V(n) asm volatile("s_waitcnt vmcnt(" #n ")" ::: "memory")
; #define PG8_WAIT_L(n) asm volatile("s_waitcnt lgkmcnt(" #n ")" ::: "memory")
; #define PG8_BAR __builtin_amdgcn_s_barrier()
; #define PG8_SCHED __builtin_amdgcn_sched_barrier(0)
; template <class Epi, bool ALIGN_EPI>
; __device__ __forceinline__ void gemm_phase(LAS unsigned char* lds, const int tid, const Gemm g, const StaticOrder& S, const Epi& E) {
;     ...
;             PG8_LDA(At, 1, 1); PG8_STAGE(PG8_SB(1, 0), b3, voffB); PG8_STAGE(PG8_SB(1, 1), b3 + hstepB, voffB); PG8_STAGE(PG8_SA(1, 0), a3, voffA);
;             PG8_WAIT_V(8); PG8_WAIT_L(0); PG8_BAR; PG8_MMA(1, 0, At, B0); PG8_MMA(1, 1, At, B1); PG8_BAR; PG8_SCHED;
;         }
;     __device__ __forceinline__ void operator()(const f32x4 (&acc)[2][2][4][2], const Unit& u, int wr, int wc, int fr, int fq) const {
;     ...
;             const int col0 = colt - ZW + wc * 32 + 8 * fq;
;             f32x4 bv[2][2];
; #pragma unroll
;             for (int bj = 0; bj < 2; ++bj)
; #pragma unroll
;                 for (int n = 0; n < 2; ++n) bv[bj][n] = *(const GAS f32x4*)(bgate + col0 + bj * HALF + 4 * n);
	s_add_i32 s24, s49, s27
	v_lshl_add_u64 v[170:171], v[170:171], 0, s[42:43]
	s_mov_b32 m0, s24
	ds_read_b128 v[182:185], v176 offset:49152
	ds_read_b128 v[186:189], v176 offset:50176
	ds_read_b128 v[190:193], v176 offset:51200
	ds_read_b128 v[208:211], v176 offset:52224
	ds_read_b128 v[212:215], v176 offset:53248
	ds_read_b128 v[216:219], v176 offset:54272
	ds_read_b128 v[220:223], v176 offset:55296
	ds_read_b128 v[240:243], v176 offset:56320
	global_load_lds_dwordx4 v[170:171], off
	s_add_i32 m0, s24, 0x2000
	s_add_u32 s22, s22, 0x80080
	v_lshl_add_u64 v[170:171], v[194:195], 0, s[42:43]
	s_addc_u32 s23, s23, 0
	s_add_i32 s24, s52, s27
	global_load_lds_dwordx4 v[170:171], off
	v_lshl_add_u64 v[170:171], s[22:23], 0, v[148:149]
	s_mov_b32 m0, s24
	s_nop 0
	global_load_lds_dwordx4 v[170:171], off
	v_lshl_add_u64 v[170:171], s[22:23], 0, v[152:153]
	s_add_i32 m0, s24, 0x2000
	s_nop 0
	global_load_lds_dwordx4 v[170:171], off
	s_waitcnt vmcnt(4)
	s_waitcnt lgkmcnt(0)
	s_barrier
	v_mfma_f32_16x16x32_bf16 v[62:65], v[130:133], v[182:185], v[62:65]
	v_mfma_f32_16x16x32_bf16 v[58:61], v[138:141], v[182:185], v[58:61]
	v_mfma_f32_16x16x32_bf16 v[54:57], v[130:133], v[190:193], v[54:57]
	v_mfma_f32_16x16x32_bf16 v[50:53], v[138:141], v[190:193], v[50:53]
	v_mfma_f32_16x16x32_bf16 v[38:41], v[130:133], v[212:215], v[38:41]
	v_mfma_f32_16x16x32_bf16 v[34:37], v[138:141], v[212:215], v[34:37]
	v_mfma_f32_16x16x32_bf16 v[22:25], v[130:133], v[220:223], v[22:25]
	v_mfma_f32_16x16x32_bf16 v[18:21], v[138:141], v[220:223], v[18:21]
	v_mfma_f32_16x16x32_bf16 v[62:65], v[134:137], v[186:189], v[62:65]
	v_mfma_f32_16x16x32_bf16 v[58:61], v[142:145], v[186:189], v[58:61]
	v_mfma_f32_16x16x32_bf16 v[54:57], v[134:137], v[208:211], v[54:57]
	v_mfma_f32_16x16x32_bf16 v[50:53], v[142:145], v[208:211], v[50:53]
	v_mfma_f32_16x16x32_bf16 v[38:41], v[134:137], v[216:219], v[38:41]
	v_mfma_f32_16x16x32_bf16 v[34:37], v[142:145], v[216:219], v[34:37]
	v_mfma_f32_16x16x32_bf16 v[22:25], v[134:137], v[240:243], v[22:25]
	v_mfma_f32_16x16x32_bf16 v[18:21], v[142:145], v[240:243], v[18:21]
	v_mfma_f32_16x16x32_bf16 v[46:49], v[158:161], v[182:185], v[46:49]
	v_mfma_f32_16x16x32_bf16 v[42:45], v[166:169], v[182:185], v[42:45]
	v_mfma_f32_16x16x32_bf16 v[30:33], v[158:161], v[190:193], v[30:33]
	v_mfma_f32_16x16x32_bf16 v[26:29], v[166:169], v[190:193], v[26:29]
	v_mfma_f32_16x16x32_bf16 v[14:17], v[158:161], v[212:215], v[14:17]
	v_mfma_f32_16x16x32_bf16 v[10:13], v[166:169], v[212:215], v[10:13]
	v_mfma_f32_16x16x32_bf16 v[6:9], v[158:161], v[220:223], v[6:9]
	v_mfma_f32_16x16x32_bf16 v[2:5], v[166:169], v[220:223], v[2:5]
	v_mfma_f32_16x16x32_bf16 v[46:49], v[162:165], v[186:189], v[46:49]
	v_mfma_f32_16x16x32_bf16 v[42:45], v[178:181], v[186:189], v[42:45]
	v_mfma_f32_16x16x32_bf16 v[30:33], v[162:165], v[208:211], v[30:33]
	v_mfma_f32_16x16x32_bf16 v[26:29], v[178:181], v[208:211], v[26:29]
	v_mfma_f32_16x16x32_bf16 v[14:17], v[162:165], v[216:219], v[14:17]
	v_mfma_f32_16x16x32_bf16 v[10:13], v[178:181], v[216:219], v[10:13]
	v_mfma_f32_16x16x32_bf16 v[6:9], v[162:165], v[240:243], v[6:9]
	v_mfma_f32_16x16x32_bf16 v[2:5], v[178:181], v[240:243], v[2:5]
	s_barrier
	s_add_i32 s19, s19, 2
	s_add_u32 s11, s11, 0x100
	s_addc_u32 s13, s13, 0
	s_add_u32 s20, s20, 0x100
	s_addc_u32 s21, s21, 0
	s_cmp_gt_u32 s19, 29
	s_cbranch_scc0 .LBB0_667
	s_lshl_b32 s11, s41, 8
	s_cmp_gt_i32 s41, 16
	s_cbranch_scc0 .Lwin_nobias
	v_add_u32_e32 v0, s11, v175
	v_lshl_add_u64 v[134:135], v[0:1], 2, s[6:7]
	global_load_dwordx4 v[138:141], v[134:135], off offset:16
	global_load_dwordx4 v[142:145], v[134:135], off
	global_load_dwordx4 v[130:133], v[134:135], off offset:528
	s_nop 0
	global_load_dwordx4 v[134:137], v[134:135], off offset:512
